# GEMM K-loops: redundant back-to-back s_setprio 0/1 pair between the two 16-MFMA halves of each 32-MFMA block removed
# speedup vs baseline: 1.0048x; 1.0023x over previous
.LBB0_224:
	s_add_u32 s44, s38, 0x100
	s_addc_u32 s45, s39, 0
	s_add_i32 s30, 0, 0x10000
	s_cmp_eq_u32 s73, 12
	s_cselect_b32 s49, s9, s45
	s_cselect_b32 s48, s11, s44
	v_add_u32_e32 v138, s30, v141
	s_cselect_b32 s47, s20, s29
	s_cselect_b32 s46, s21, s27
	s_add_i32 s83, 0, 0x14000
	ds_read_b128 v[148:151], v138
	ds_read_b128 v[152:155], v138 offset:1024
	ds_read_b128 v[156:159], v138 offset:2048
	ds_read_b128 v[160:163], v138 offset:3072
	v_add_u32_e32 v138, s83, v141
	ds_read_b128 v[164:167], v138
	ds_read_b128 v[168:171], v138 offset:1024
	ds_read_b128 v[172:175], v138 offset:2048
	ds_read_b128 v[198:201], v138 offset:3072
	v_lshl_add_u64 v[138:139], s[38:39], 0, v[136:137]
	s_add_i32 m0, s40, 0xc000
	ds_read_b128 v[202:205], v145
	ds_read_b128 v[206:209], v145 offset:1024
	ds_read_b128 v[210:213], v145 offset:2048
	ds_read_b128 v[214:217], v145 offset:3072
	ds_read_b128 v[218:221], v145 offset:4096
	ds_read_b128 v[222:225], v145 offset:5120
	ds_read_b128 v[226:229], v145 offset:6144
	ds_read_b128 v[238:241], v145 offset:7168
	global_load_lds_dwordx4 v[138:139], off
	v_lshl_add_u64 v[138:139], s[38:39], 0, v[134:135]
	s_add_i32 m0, s40, 0xe000
	s_nop 0
	global_load_lds_dwordx4 v[138:139], off
	s_waitcnt vmcnt(8)
	s_waitcnt lgkmcnt(0)
	s_barrier
	s_setprio 1
	s_waitcnt lgkmcnt(0)
	v_mfma_f32_16x16x32_bf16 v[124:127], v[148:151], v[202:205], v[124:127]
	v_mfma_f32_16x16x32_bf16 v[120:123], v[156:159], v[202:205], v[120:123]
	v_mfma_f32_16x16x32_bf16 v[116:119], v[148:151], v[210:213], v[116:119]
	v_mfma_f32_16x16x32_bf16 v[112:115], v[156:159], v[210:213], v[112:115]
	v_mfma_f32_16x16x32_bf16 v[108:111], v[148:151], v[218:221], v[108:111]
	v_mfma_f32_16x16x32_bf16 v[104:107], v[156:159], v[218:221], v[104:107]
	v_mfma_f32_16x16x32_bf16 v[100:103], v[148:151], v[226:229], v[100:103]
	v_mfma_f32_16x16x32_bf16 v[96:99], v[156:159], v[226:229], v[96:99]
	v_mfma_f32_16x16x32_bf16 v[124:127], v[152:155], v[206:209], v[124:127]
	v_mfma_f32_16x16x32_bf16 v[120:123], v[160:163], v[206:209], v[120:123]
	v_mfma_f32_16x16x32_bf16 v[116:119], v[152:155], v[214:217], v[116:119]
	v_mfma_f32_16x16x32_bf16 v[112:115], v[160:163], v[214:217], v[112:115]
	v_mfma_f32_16x16x32_bf16 v[108:111], v[152:155], v[222:225], v[108:111]
	v_mfma_f32_16x16x32_bf16 v[104:107], v[160:163], v[222:225], v[104:107]
	v_mfma_f32_16x16x32_bf16 v[100:103], v[152:155], v[238:241], v[100:103]
	v_mfma_f32_16x16x32_bf16 v[96:99], v[160:163], v[238:241], v[96:99]
	v_mfma_f32_16x16x32_bf16 v[60:63], v[164:167], v[202:205], v[60:63]
	v_mfma_f32_16x16x32_bf16 v[56:59], v[172:175], v[202:205], v[56:59]
	v_mfma_f32_16x16x32_bf16 v[52:55], v[164:167], v[210:213], v[52:55]
	v_mfma_f32_16x16x32_bf16 v[48:51], v[172:175], v[210:213], v[48:51]
	v_mfma_f32_16x16x32_bf16 v[44:47], v[164:167], v[218:221], v[44:47]
	v_mfma_f32_16x16x32_bf16 v[40:43], v[172:175], v[218:221], v[40:43]
	v_mfma_f32_16x16x32_bf16 v[36:39], v[164:167], v[226:229], v[36:39]
	v_mfma_f32_16x16x32_bf16 v[32:35], v[172:175], v[226:229], v[32:35]
	v_mfma_f32_16x16x32_bf16 v[60:63], v[168:171], v[206:209], v[60:63]
	v_mfma_f32_16x16x32_bf16 v[56:59], v[198:201], v[206:209], v[56:59]
	v_mfma_f32_16x16x32_bf16 v[52:55], v[168:171], v[214:217], v[52:55]
	v_mfma_f32_16x16x32_bf16 v[48:51], v[198:201], v[214:217], v[48:51]
	v_mfma_f32_16x16x32_bf16 v[44:47], v[168:171], v[222:225], v[44:47]
	v_mfma_f32_16x16x32_bf16 v[40:43], v[198:201], v[222:225], v[40:43]
	v_mfma_f32_16x16x32_bf16 v[36:39], v[168:171], v[238:241], v[36:39]
	v_mfma_f32_16x16x32_bf16 v[32:35], v[198:201], v[238:241], v[32:35]
	s_setprio 0
	s_barrier
	s_add_i32 s30, s30, s5
	v_lshl_add_u64 v[138:139], s[46:47], 0, v[130:131]
	s_mov_b32 m0, s30
	ds_read_b128 v[202:205], v145 offset:16384
	ds_read_b128 v[206:209], v145 offset:17408
	ds_read_b128 v[210:213], v145 offset:18432
	ds_read_b128 v[214:217], v145 offset:19456
	ds_read_b128 v[218:221], v145 offset:20480
	ds_read_b128 v[222:225], v145 offset:21504
	ds_read_b128 v[226:229], v145 offset:22528
	ds_read_b128 v[238:241], v145 offset:23552
	global_load_lds_dwordx4 v[138:139], off
	s_add_i32 m0, s30, 0x2000
	s_add_u32 s30, s46, 0x40000
	v_lshl_add_u64 v[176:177], s[46:47], 0, v[132:133]
	s_addc_u32 s31, s47, 0
	s_add_i32 s38, s83, s5
	global_load_lds_dwordx4 v[176:177], off
	v_lshl_add_u64 v[242:243], s[30:31], 0, v[130:131]
	s_mov_b32 m0, s38
	v_lshl_add_u64 v[244:245], s[48:49], 0, v[132:133]
	global_load_lds_dwordx4 v[242:243], off
	v_lshl_add_u64 v[242:243], s[30:31], 0, v[132:133]
	s_add_i32 m0, s38, 0x2000
	s_nop 0
	global_load_lds_dwordx4 v[242:243], off
	v_lshl_add_u64 v[242:243], s[48:49], 0, v[130:131]
	s_mov_b32 m0, s40
	s_nop 0
	global_load_lds_dwordx4 v[242:243], off
	s_mov_b32 m0, s41
	s_nop 0
	global_load_lds_dwordx4 v[244:245], off
	s_waitcnt vmcnt(8)
	s_waitcnt lgkmcnt(0)
	s_barrier
	s_setprio 1
	s_waitcnt lgkmcnt(0)
	v_mfma_f32_16x16x32_bf16 v[92:95], v[148:151], v[202:205], v[92:95]
	v_mfma_f32_16x16x32_bf16 v[88:91], v[156:159], v[202:205], v[88:91]
	v_mfma_f32_16x16x32_bf16 v[84:87], v[148:151], v[210:213], v[84:87]
	v_mfma_f32_16x16x32_bf16 v[80:83], v[156:159], v[210:213], v[80:83]
	v_mfma_f32_16x16x32_bf16 v[76:79], v[148:151], v[218:221], v[76:79]
	v_mfma_f32_16x16x32_bf16 v[72:75], v[156:159], v[218:221], v[72:75]
	v_mfma_f32_16x16x32_bf16 v[68:71], v[148:151], v[226:229], v[68:71]
	v_mfma_f32_16x16x32_bf16 v[64:67], v[156:159], v[226:229], v[64:67]
	v_mfma_f32_16x16x32_bf16 v[92:95], v[152:155], v[206:209], v[92:95]
	v_mfma_f32_16x16x32_bf16 v[88:91], v[160:163], v[206:209], v[88:91]
	v_mfma_f32_16x16x32_bf16 v[84:87], v[152:155], v[214:217], v[84:87]
	v_mfma_f32_16x16x32_bf16 v[80:83], v[160:163], v[214:217], v[80:83]
	v_mfma_f32_16x16x32_bf16 v[76:79], v[152:155], v[222:225], v[76:79]
	v_mfma_f32_16x16x32_bf16 v[72:75], v[160:163], v[222:225], v[72:75]
	v_mfma_f32_16x16x32_bf16 v[68:71], v[152:155], v[238:241], v[68:71]
	v_mfma_f32_16x16x32_bf16 v[64:67], v[160:163], v[238:241], v[64:67]
	v_mfma_f32_16x16x32_bf16 v[28:31], v[164:167], v[202:205], v[28:31]
	v_mfma_f32_16x16x32_bf16 v[24:27], v[172:175], v[202:205], v[24:27]
	v_mfma_f32_16x16x32_bf16 v[20:23], v[164:167], v[210:213], v[20:23]
	v_mfma_f32_16x16x32_bf16 v[16:19], v[172:175], v[210:213], v[16:19]
	v_mfma_f32_16x16x32_bf16 v[12:15], v[164:167], v[218:221], v[12:15]
	v_mfma_f32_16x16x32_bf16 v[8:11], v[172:175], v[218:221], v[8:11]
	v_mfma_f32_16x16x32_bf16 v[4:7], v[164:167], v[226:229], v[4:7]
	v_mfma_f32_16x16x32_bf16 v[0:3], v[172:175], v[226:229], v[0:3]
	v_mfma_f32_16x16x32_bf16 v[28:31], v[168:171], v[206:209], v[28:31]
	v_mfma_f32_16x16x32_bf16 v[24:27], v[198:201], v[206:209], v[24:27]
	v_mfma_f32_16x16x32_bf16 v[20:23], v[168:171], v[214:217], v[20:23]
	v_mfma_f32_16x16x32_bf16 v[16:19], v[198:201], v[214:217], v[16:19]
	v_mfma_f32_16x16x32_bf16 v[12:15], v[168:171], v[222:225], v[12:15]
	v_mfma_f32_16x16x32_bf16 v[8:11], v[198:201], v[222:225], v[8:11]
	v_mfma_f32_16x16x32_bf16 v[4:7], v[168:171], v[238:241], v[4:7]
	v_mfma_f32_16x16x32_bf16 v[0:3], v[198:201], v[238:241], v[0:3]
	s_setprio 0
	s_barrier
	s_add_i32 s38, 0, 0x18000
	v_add_u32_e32 v147, s38, v141
	s_add_i32 s39, 0, 0x1c000
	ds_read_b128 v[148:151], v147
	ds_read_b128 v[152:155], v147 offset:1024
	ds_read_b128 v[156:159], v147 offset:2048
	ds_read_b128 v[160:163], v147 offset:3072
	v_add_u32_e32 v147, s39, v141
	ds_read_b128 v[164:167], v147
	ds_read_b128 v[168:171], v147 offset:1024
	ds_read_b128 v[172:175], v147 offset:2048
	ds_read_b128 v[198:201], v147 offset:3072
	s_add_u32 s30, s48, 0x40000
	s_addc_u32 s31, s49, 0
	s_mov_b32 m0, s42
	v_lshl_add_u64 v[246:247], s[30:31], 0, v[130:131]
	ds_read_b128 v[202:205], v145 offset:32768
	ds_read_b128 v[206:209], v145 offset:33792
	ds_read_b128 v[210:213], v145 offset:34816
	ds_read_b128 v[214:217], v145 offset:35840
	ds_read_b128 v[218:221], v145 offset:36864
	ds_read_b128 v[222:225], v145 offset:37888
	ds_read_b128 v[226:229], v145 offset:38912
	ds_read_b128 v[238:241], v145 offset:39936
	global_load_lds_dwordx4 v[246:247], off
	v_lshl_add_u64 v[246:247], s[30:31], 0, v[132:133]
	s_mov_b32 m0, s43
	s_nop 0
	global_load_lds_dwordx4 v[246:247], off
	s_waitcnt vmcnt(8)
	s_waitcnt lgkmcnt(0)
	s_barrier
	s_setprio 1
	s_waitcnt lgkmcnt(0)
	v_mfma_f32_16x16x32_bf16 v[124:127], v[148:151], v[202:205], v[124:127]
	v_mfma_f32_16x16x32_bf16 v[120:123], v[156:159], v[202:205], v[120:123]
	v_mfma_f32_16x16x32_bf16 v[116:119], v[148:151], v[210:213], v[116:119]
	v_mfma_f32_16x16x32_bf16 v[112:115], v[156:159], v[210:213], v[112:115]
	v_mfma_f32_16x16x32_bf16 v[108:111], v[148:151], v[218:221], v[108:111]
	v_mfma_f32_16x16x32_bf16 v[104:107], v[156:159], v[218:221], v[104:107]
	v_mfma_f32_16x16x32_bf16 v[100:103], v[148:151], v[226:229], v[100:103]
	v_mfma_f32_16x16x32_bf16 v[96:99], v[156:159], v[226:229], v[96:99]
	v_mfma_f32_16x16x32_bf16 v[124:127], v[152:155], v[206:209], v[124:127]
	v_mfma_f32_16x16x32_bf16 v[120:123], v[160:163], v[206:209], v[120:123]
	v_mfma_f32_16x16x32_bf16 v[116:119], v[152:155], v[214:217], v[116:119]
	v_mfma_f32_16x16x32_bf16 v[112:115], v[160:163], v[214:217], v[112:115]
	v_mfma_f32_16x16x32_bf16 v[108:111], v[152:155], v[222:225], v[108:111]
	v_mfma_f32_16x16x32_bf16 v[104:107], v[160:163], v[222:225], v[104:107]
	v_mfma_f32_16x16x32_bf16 v[100:103], v[152:155], v[238:241], v[100:103]
	v_mfma_f32_16x16x32_bf16 v[96:99], v[160:163], v[238:241], v[96:99]
	v_mfma_f32_16x16x32_bf16 v[60:63], v[164:167], v[202:205], v[60:63]
	v_mfma_f32_16x16x32_bf16 v[56:59], v[172:175], v[202:205], v[56:59]
	v_mfma_f32_16x16x32_bf16 v[52:55], v[164:167], v[210:213], v[52:55]
	v_mfma_f32_16x16x32_bf16 v[48:51], v[172:175], v[210:213], v[48:51]
	v_mfma_f32_16x16x32_bf16 v[44:47], v[164:167], v[218:221], v[44:47]
	v_mfma_f32_16x16x32_bf16 v[40:43], v[172:175], v[218:221], v[40:43]
	v_mfma_f32_16x16x32_bf16 v[36:39], v[164:167], v[226:229], v[36:39]
	v_mfma_f32_16x16x32_bf16 v[32:35], v[172:175], v[226:229], v[32:35]
	v_mfma_f32_16x16x32_bf16 v[60:63], v[168:171], v[206:209], v[60:63]
	v_mfma_f32_16x16x32_bf16 v[56:59], v[198:201], v[206:209], v[56:59]
	v_mfma_f32_16x16x32_bf16 v[52:55], v[168:171], v[214:217], v[52:55]
	v_mfma_f32_16x16x32_bf16 v[48:51], v[198:201], v[214:217], v[48:51]
	v_mfma_f32_16x16x32_bf16 v[44:47], v[168:171], v[222:225], v[44:47]
	v_mfma_f32_16x16x32_bf16 v[40:43], v[198:201], v[222:225], v[40:43]
	v_mfma_f32_16x16x32_bf16 v[36:39], v[168:171], v[238:241], v[36:39]
	v_mfma_f32_16x16x32_bf16 v[32:35], v[198:201], v[238:241], v[32:35]
	s_setprio 0
	s_barrier
	s_add_i32 s30, s38, s5
	v_lshl_add_u64 v[138:139], v[138:139], 0, s[90:91]
	s_mov_b32 m0, s30
	ds_read_b128 v[202:205], v145 offset:49152
	ds_read_b128 v[206:209], v145 offset:50176
	ds_read_b128 v[210:213], v145 offset:51200
	ds_read_b128 v[214:217], v145 offset:52224
	ds_read_b128 v[218:221], v145 offset:53248
	ds_read_b128 v[222:225], v145 offset:54272
	ds_read_b128 v[226:229], v145 offset:55296
	ds_read_b128 v[238:241], v145 offset:56320
	global_load_lds_dwordx4 v[138:139], off
	s_add_i32 m0, s30, 0x2000
	s_add_u32 s30, s46, 0x40080
	v_lshl_add_u64 v[138:139], v[176:177], 0, s[90:91]
	s_addc_u32 s31, s47, 0
	s_add_i32 s38, s39, s5
	global_load_lds_dwordx4 v[138:139], off
	v_lshl_add_u64 v[138:139], s[30:31], 0, v[130:131]
	s_mov_b32 m0, s38
	s_nop 0
	global_load_lds_dwordx4 v[138:139], off
	v_lshl_add_u64 v[138:139], s[30:31], 0, v[132:133]
	s_add_i32 m0, s38, 0x2000
	s_nop 0
	global_load_lds_dwordx4 v[138:139], off
	v_lshl_add_u64 v[138:139], v[242:243], 0, s[90:91]
	s_mov_b32 m0, s55
	s_nop 0
	global_load_lds_dwordx4 v[138:139], off
	v_lshl_add_u64 v[138:139], v[244:245], 0, s[90:91]
	s_mov_b32 m0, s56
	s_nop 0
	global_load_lds_dwordx4 v[138:139], off
	s_waitcnt vmcnt(8)
	s_waitcnt lgkmcnt(0)
	s_barrier
	s_setprio 1
	s_waitcnt lgkmcnt(0)
	v_mfma_f32_16x16x32_bf16 v[92:95], v[148:151], v[202:205], v[92:95]
	v_mfma_f32_16x16x32_bf16 v[88:91], v[156:159], v[202:205], v[88:91]
	v_mfma_f32_16x16x32_bf16 v[84:87], v[148:151], v[210:213], v[84:87]
	v_mfma_f32_16x16x32_bf16 v[80:83], v[156:159], v[210:213], v[80:83]
	v_mfma_f32_16x16x32_bf16 v[76:79], v[148:151], v[218:221], v[76:79]
	v_mfma_f32_16x16x32_bf16 v[72:75], v[156:159], v[218:221], v[72:75]
	v_mfma_f32_16x16x32_bf16 v[68:71], v[148:151], v[226:229], v[68:71]
	v_mfma_f32_16x16x32_bf16 v[64:67], v[156:159], v[226:229], v[64:67]
	v_mfma_f32_16x16x32_bf16 v[92:95], v[152:155], v[206:209], v[92:95]
	v_mfma_f32_16x16x32_bf16 v[88:91], v[160:163], v[206:209], v[88:91]
	v_mfma_f32_16x16x32_bf16 v[84:87], v[152:155], v[214:217], v[84:87]
	v_mfma_f32_16x16x32_bf16 v[80:83], v[160:163], v[214:217], v[80:83]
	v_mfma_f32_16x16x32_bf16 v[76:79], v[152:155], v[222:225], v[76:79]
	v_mfma_f32_16x16x32_bf16 v[72:75], v[160:163], v[222:225], v[72:75]
	v_mfma_f32_16x16x32_bf16 v[68:71], v[152:155], v[238:241], v[68:71]
	v_mfma_f32_16x16x32_bf16 v[64:67], v[160:163], v[238:241], v[64:67]
	v_mfma_f32_16x16x32_bf16 v[28:31], v[164:167], v[202:205], v[28:31]
	v_mfma_f32_16x16x32_bf16 v[24:27], v[172:175], v[202:205], v[24:27]
	v_mfma_f32_16x16x32_bf16 v[20:23], v[164:167], v[210:213], v[20:23]
	v_mfma_f32_16x16x32_bf16 v[16:19], v[172:175], v[210:213], v[16:19]
	v_mfma_f32_16x16x32_bf16 v[12:15], v[164:167], v[218:221], v[12:15]
	v_mfma_f32_16x16x32_bf16 v[8:11], v[172:175], v[218:221], v[8:11]
	v_mfma_f32_16x16x32_bf16 v[4:7], v[164:167], v[226:229], v[4:7]
	v_mfma_f32_16x16x32_bf16 v[0:3], v[172:175], v[226:229], v[0:3]
	v_mfma_f32_16x16x32_bf16 v[28:31], v[168:171], v[206:209], v[28:31]
	v_mfma_f32_16x16x32_bf16 v[24:27], v[198:201], v[206:209], v[24:27]
	v_mfma_f32_16x16x32_bf16 v[20:23], v[168:171], v[214:217], v[20:23]
	v_mfma_f32_16x16x32_bf16 v[16:19], v[198:201], v[214:217], v[16:19]
	v_mfma_f32_16x16x32_bf16 v[12:15], v[168:171], v[222:225], v[12:15]
	v_mfma_f32_16x16x32_bf16 v[8:11], v[198:201], v[222:225], v[8:11]
	v_mfma_f32_16x16x32_bf16 v[4:7], v[168:171], v[238:241], v[4:7]
	v_mfma_f32_16x16x32_bf16 v[0:3], v[198:201], v[238:241], v[0:3]
	s_setprio 0
	s_barrier
	s_add_i32 s73, s73, 2
	s_add_u32 s27, s27, 0x100
	s_addc_u32 s29, s29, 0
	s_cmp_gt_u32 s73, 13
	s_mov_b64 s[38:39], s[44:45]
	s_cbranch_scc0 .LBB0_224
	s_and_b64 vcc, exec, s[24:25]
	s_cbranch_vccz .LBB0_227
	s_barrier

.LBB0_273:
	s_add_u32 s30, s28, 0xfffc0080
	s_addc_u32 s31, s29, -1
	s_add_i32 s59, 0, 0x10000
	s_cmp_eq_u32 s58, 12
	s_cselect_b32 s45, s27, s31
	s_cselect_b32 s44, s53, s30
	v_add_u32_e32 v142, s59, v145
	s_cselect_b32 s35, s25, s57
	s_cselect_b32 s34, s55, s56
	s_add_i32 s60, 0, 0x14000
	ds_read_b128 v[146:149], v142
	ds_read_b128 v[150:153], v142 offset:1024
	ds_read_b128 v[154:157], v142 offset:2048
	ds_read_b128 v[158:161], v142 offset:3072
	v_add_u32_e32 v142, s60, v145
	ds_read_b128 v[162:165], v142
	ds_read_b128 v[166:169], v142 offset:1024
	ds_read_b128 v[170:173], v142 offset:2048
	ds_read_b128 v[174:177], v142 offset:3072
	v_lshl_add_u64 v[142:143], s[28:29], 0, v[138:139]
	s_add_i32 m0, s19, 0xc000
	ds_read_b128 v[198:201], v141
	ds_read_b128 v[202:205], v141 offset:1024
	ds_read_b128 v[206:209], v141 offset:2048
	ds_read_b128 v[210:213], v141 offset:3072
	ds_read_b128 v[214:217], v141 offset:4096
	ds_read_b128 v[218:221], v141 offset:5120
	ds_read_b128 v[222:225], v141 offset:6144
	ds_read_b128 v[226:229], v141 offset:7168
	global_load_lds_dwordx4 v[142:143], off
	v_lshl_add_u64 v[142:143], s[28:29], 0, v[136:137]
	s_add_i32 m0, s19, 0xe000
	s_nop 0
	global_load_lds_dwordx4 v[142:143], off
	s_waitcnt vmcnt(8)
	s_waitcnt lgkmcnt(0)
	s_barrier
	s_setprio 1
	s_waitcnt lgkmcnt(0)
	v_mfma_f32_16x16x32_bf16 v[108:111], v[146:149], v[198:201], v[108:111]
	v_mfma_f32_16x16x32_bf16 v[116:119], v[154:157], v[198:201], v[116:119]
	v_mfma_f32_16x16x32_bf16 v[92:95], v[146:149], v[206:209], v[92:95]
	v_mfma_f32_16x16x32_bf16 v[100:103], v[154:157], v[206:209], v[100:103]
	v_mfma_f32_16x16x32_bf16 v[68:71], v[146:149], v[214:217], v[68:71]
	v_mfma_f32_16x16x32_bf16 v[76:79], v[154:157], v[214:217], v[76:79]
	v_mfma_f32_16x16x32_bf16 v[40:43], v[146:149], v[222:225], v[40:43]
	v_mfma_f32_16x16x32_bf16 v[44:47], v[154:157], v[222:225], v[44:47]
	v_mfma_f32_16x16x32_bf16 v[108:111], v[150:153], v[202:205], v[108:111]
	v_mfma_f32_16x16x32_bf16 v[116:119], v[158:161], v[202:205], v[116:119]
	v_mfma_f32_16x16x32_bf16 v[92:95], v[150:153], v[210:213], v[92:95]
	v_mfma_f32_16x16x32_bf16 v[100:103], v[158:161], v[210:213], v[100:103]
	v_mfma_f32_16x16x32_bf16 v[68:71], v[150:153], v[218:221], v[68:71]
	v_mfma_f32_16x16x32_bf16 v[76:79], v[158:161], v[218:221], v[76:79]
	v_mfma_f32_16x16x32_bf16 v[40:43], v[150:153], v[226:229], v[40:43]
	v_mfma_f32_16x16x32_bf16 v[44:47], v[158:161], v[226:229], v[44:47]
	v_mfma_f32_16x16x32_bf16 v[120:123], v[162:165], v[198:201], v[120:123]
	v_mfma_f32_16x16x32_bf16 v[124:127], v[170:173], v[198:201], v[124:127]
	v_mfma_f32_16x16x32_bf16 v[104:107], v[162:165], v[206:209], v[104:107]
	v_mfma_f32_16x16x32_bf16 v[112:115], v[170:173], v[206:209], v[112:115]
	v_mfma_f32_16x16x32_bf16 v[88:91], v[162:165], v[214:217], v[88:91]
	v_mfma_f32_16x16x32_bf16 v[96:99], v[170:173], v[214:217], v[96:99]
	v_mfma_f32_16x16x32_bf16 v[64:67], v[162:165], v[222:225], v[64:67]
	v_mfma_f32_16x16x32_bf16 v[72:75], v[170:173], v[222:225], v[72:75]
	v_mfma_f32_16x16x32_bf16 v[120:123], v[166:169], v[202:205], v[120:123]
	v_mfma_f32_16x16x32_bf16 v[124:127], v[174:177], v[202:205], v[124:127]
	v_mfma_f32_16x16x32_bf16 v[104:107], v[166:169], v[210:213], v[104:107]
	v_mfma_f32_16x16x32_bf16 v[112:115], v[174:177], v[210:213], v[112:115]
	v_mfma_f32_16x16x32_bf16 v[88:91], v[166:169], v[218:221], v[88:91]
	v_mfma_f32_16x16x32_bf16 v[96:99], v[174:177], v[218:221], v[96:99]
	v_mfma_f32_16x16x32_bf16 v[64:67], v[166:169], v[226:229], v[64:67]
	v_mfma_f32_16x16x32_bf16 v[72:75], v[174:177], v[226:229], v[72:75]
	s_setprio 0
	s_barrier
	s_add_i32 s30, s59, s4
	v_lshl_add_u64 v[142:143], s[34:35], 0, v[128:129]
	s_mov_b32 m0, s30
	ds_read_b128 v[198:201], v141 offset:16384
	ds_read_b128 v[202:205], v141 offset:17408
	ds_read_b128 v[206:209], v141 offset:18432
	ds_read_b128 v[210:213], v141 offset:19456
	ds_read_b128 v[214:217], v141 offset:20480
	ds_read_b128 v[218:221], v141 offset:21504
	ds_read_b128 v[222:225], v141 offset:22528
	ds_read_b128 v[226:229], v141 offset:23552
	global_load_lds_dwordx4 v[142:143], off
	s_add_i32 m0, s30, 0x2000
	s_add_u32 s30, s34, 0x40000
	v_lshl_add_u64 v[238:239], s[34:35], 0, v[130:131]
	s_addc_u32 s31, s35, 0
	s_add_i32 s59, s60, s4
	global_load_lds_dwordx4 v[238:239], off
	v_lshl_add_u64 v[240:241], s[30:31], 0, v[128:129]
	s_mov_b32 m0, s59
	v_lshl_add_u64 v[242:243], s[44:45], 0, v[132:133]
	global_load_lds_dwordx4 v[240:241], off
	v_lshl_add_u64 v[240:241], s[30:31], 0, v[130:131]
	s_add_i32 m0, s59, 0x2000
	s_nop 0
	global_load_lds_dwordx4 v[240:241], off
	v_lshl_add_u64 v[240:241], s[44:45], 0, v[134:135]
	s_mov_b32 m0, s19
	s_nop 0
	global_load_lds_dwordx4 v[240:241], off
	s_mov_b32 m0, s43
	s_nop 0
	global_load_lds_dwordx4 v[242:243], off
	s_waitcnt vmcnt(8)
	s_waitcnt lgkmcnt(0)
	s_barrier
	s_setprio 1
	s_waitcnt lgkmcnt(0)
	v_mfma_f32_16x16x32_bf16 v[52:55], v[146:149], v[198:201], v[52:55]
	v_mfma_f32_16x16x32_bf16 v[60:63], v[154:157], v[198:201], v[60:63]
	v_mfma_f32_16x16x32_bf16 v[28:31], v[146:149], v[206:209], v[28:31]
	v_mfma_f32_16x16x32_bf16 v[36:39], v[154:157], v[206:209], v[36:39]
	v_mfma_f32_16x16x32_bf16 v[12:15], v[146:149], v[214:217], v[12:15]
	v_mfma_f32_16x16x32_bf16 v[16:19], v[154:157], v[214:217], v[16:19]
	v_mfma_f32_16x16x32_bf16 v[0:3], v[146:149], v[222:225], v[0:3]
	v_mfma_f32_16x16x32_bf16 v[4:7], v[154:157], v[222:225], v[4:7]
	v_mfma_f32_16x16x32_bf16 v[52:55], v[150:153], v[202:205], v[52:55]
	v_mfma_f32_16x16x32_bf16 v[60:63], v[158:161], v[202:205], v[60:63]
	v_mfma_f32_16x16x32_bf16 v[28:31], v[150:153], v[210:213], v[28:31]
	v_mfma_f32_16x16x32_bf16 v[36:39], v[158:161], v[210:213], v[36:39]
	v_mfma_f32_16x16x32_bf16 v[12:15], v[150:153], v[218:221], v[12:15]
	v_mfma_f32_16x16x32_bf16 v[16:19], v[158:161], v[218:221], v[16:19]
	v_mfma_f32_16x16x32_bf16 v[0:3], v[150:153], v[226:229], v[0:3]
	v_mfma_f32_16x16x32_bf16 v[4:7], v[158:161], v[226:229], v[4:7]
	v_mfma_f32_16x16x32_bf16 v[80:83], v[162:165], v[198:201], v[80:83]
	v_mfma_f32_16x16x32_bf16 v[84:87], v[170:173], v[198:201], v[84:87]
	v_mfma_f32_16x16x32_bf16 v[48:51], v[162:165], v[206:209], v[48:51]
	v_mfma_f32_16x16x32_bf16 v[56:59], v[170:173], v[206:209], v[56:59]
	v_mfma_f32_16x16x32_bf16 v[24:27], v[162:165], v[214:217], v[24:27]
	v_mfma_f32_16x16x32_bf16 v[32:35], v[170:173], v[214:217], v[32:35]
	v_mfma_f32_16x16x32_bf16 v[8:11], v[162:165], v[222:225], v[8:11]
	v_mfma_f32_16x16x32_bf16 v[20:23], v[170:173], v[222:225], v[20:23]
	v_mfma_f32_16x16x32_bf16 v[80:83], v[166:169], v[202:205], v[80:83]
	v_mfma_f32_16x16x32_bf16 v[84:87], v[174:177], v[202:205], v[84:87]
	v_mfma_f32_16x16x32_bf16 v[48:51], v[166:169], v[210:213], v[48:51]
	v_mfma_f32_16x16x32_bf16 v[56:59], v[174:177], v[210:213], v[56:59]
	v_mfma_f32_16x16x32_bf16 v[24:27], v[166:169], v[218:221], v[24:27]
	v_mfma_f32_16x16x32_bf16 v[32:35], v[174:177], v[218:221], v[32:35]
	v_mfma_f32_16x16x32_bf16 v[8:11], v[166:169], v[226:229], v[8:11]
	v_mfma_f32_16x16x32_bf16 v[20:23], v[174:177], v[226:229], v[20:23]
	s_setprio 0
	s_barrier
	s_add_i32 s59, 0, 0x18000
	s_add_i32 s60, 0, 0x1c000
	v_add_u32_e32 v158, s59, v145
	v_add_u32_e32 v174, s60, v145
	ds_read_b128 v[146:149], v158
	ds_read_b128 v[150:153], v158 offset:1024
	ds_read_b128 v[154:157], v158 offset:2048
	ds_read_b128 v[158:161], v158 offset:3072
	ds_read_b128 v[162:165], v174
	ds_read_b128 v[166:169], v174 offset:1024
	ds_read_b128 v[170:173], v174 offset:2048
	ds_read_b128 v[174:177], v174 offset:3072
	s_add_u32 s30, s44, 0x40000
	s_addc_u32 s31, s45, 0
	s_mov_b32 m0, s46
	v_lshl_add_u64 v[244:245], s[30:31], 0, v[134:135]
	ds_read_b128 v[198:201], v141 offset:32768
	ds_read_b128 v[202:205], v141 offset:33792
	ds_read_b128 v[206:209], v141 offset:34816
	ds_read_b128 v[210:213], v141 offset:35840
	ds_read_b128 v[214:217], v141 offset:36864
	ds_read_b128 v[218:221], v141 offset:37888
	ds_read_b128 v[222:225], v141 offset:38912
	ds_read_b128 v[226:229], v141 offset:39936
	global_load_lds_dwordx4 v[244:245], off
	v_lshl_add_u64 v[244:245], s[30:31], 0, v[132:133]
	s_mov_b32 m0, s47
	s_nop 0
	global_load_lds_dwordx4 v[244:245], off
	s_waitcnt vmcnt(8)
	s_waitcnt lgkmcnt(0)
	s_barrier
	s_setprio 1
	s_waitcnt lgkmcnt(0)
	v_mfma_f32_16x16x32_bf16 v[108:111], v[146:149], v[198:201], v[108:111]
	v_mfma_f32_16x16x32_bf16 v[116:119], v[154:157], v[198:201], v[116:119]
	v_mfma_f32_16x16x32_bf16 v[92:95], v[146:149], v[206:209], v[92:95]
	v_mfma_f32_16x16x32_bf16 v[100:103], v[154:157], v[206:209], v[100:103]
	v_mfma_f32_16x16x32_bf16 v[68:71], v[146:149], v[214:217], v[68:71]
	v_mfma_f32_16x16x32_bf16 v[76:79], v[154:157], v[214:217], v[76:79]
	v_mfma_f32_16x16x32_bf16 v[40:43], v[146:149], v[222:225], v[40:43]
	v_mfma_f32_16x16x32_bf16 v[44:47], v[154:157], v[222:225], v[44:47]
	v_mfma_f32_16x16x32_bf16 v[108:111], v[150:153], v[202:205], v[108:111]
	v_mfma_f32_16x16x32_bf16 v[116:119], v[158:161], v[202:205], v[116:119]
	v_mfma_f32_16x16x32_bf16 v[92:95], v[150:153], v[210:213], v[92:95]
	v_mfma_f32_16x16x32_bf16 v[100:103], v[158:161], v[210:213], v[100:103]
	v_mfma_f32_16x16x32_bf16 v[68:71], v[150:153], v[218:221], v[68:71]
	v_mfma_f32_16x16x32_bf16 v[76:79], v[158:161], v[218:221], v[76:79]
	v_mfma_f32_16x16x32_bf16 v[40:43], v[150:153], v[226:229], v[40:43]
	v_mfma_f32_16x16x32_bf16 v[44:47], v[158:161], v[226:229], v[44:47]
	v_mfma_f32_16x16x32_bf16 v[120:123], v[162:165], v[198:201], v[120:123]
	v_mfma_f32_16x16x32_bf16 v[124:127], v[170:173], v[198:201], v[124:127]
	v_mfma_f32_16x16x32_bf16 v[104:107], v[162:165], v[206:209], v[104:107]
	v_mfma_f32_16x16x32_bf16 v[112:115], v[170:173], v[206:209], v[112:115]
	v_mfma_f32_16x16x32_bf16 v[88:91], v[162:165], v[214:217], v[88:91]
	v_mfma_f32_16x16x32_bf16 v[96:99], v[170:173], v[214:217], v[96:99]
	v_mfma_f32_16x16x32_bf16 v[64:67], v[162:165], v[222:225], v[64:67]
	v_mfma_f32_16x16x32_bf16 v[72:75], v[170:173], v[222:225], v[72:75]
	v_mfma_f32_16x16x32_bf16 v[120:123], v[166:169], v[202:205], v[120:123]
	v_mfma_f32_16x16x32_bf16 v[124:127], v[174:177], v[202:205], v[124:127]
	v_mfma_f32_16x16x32_bf16 v[104:107], v[166:169], v[210:213], v[104:107]
	v_mfma_f32_16x16x32_bf16 v[112:115], v[174:177], v[210:213], v[112:115]
	v_mfma_f32_16x16x32_bf16 v[88:91], v[166:169], v[218:221], v[88:91]
	v_mfma_f32_16x16x32_bf16 v[96:99], v[174:177], v[218:221], v[96:99]
	v_mfma_f32_16x16x32_bf16 v[64:67], v[166:169], v[226:229], v[64:67]
	v_mfma_f32_16x16x32_bf16 v[72:75], v[174:177], v[226:229], v[72:75]
	s_setprio 0
	s_barrier
	s_add_i32 s30, s59, s4
	v_lshl_add_u64 v[142:143], v[142:143], 0, s[90:91]
	s_mov_b32 m0, s30
	ds_read_b128 v[198:201], v141 offset:49152
	ds_read_b128 v[202:205], v141 offset:50176
	ds_read_b128 v[206:209], v141 offset:51200
	ds_read_b128 v[210:213], v141 offset:52224
	ds_read_b128 v[214:217], v141 offset:53248
	ds_read_b128 v[218:221], v141 offset:54272
	ds_read_b128 v[222:225], v141 offset:55296
	ds_read_b128 v[226:229], v141 offset:56320
	global_load_lds_dwordx4 v[142:143], off
	s_add_i32 m0, s30, 0x2000
	s_add_u32 s30, s34, 0x40080
	v_lshl_add_u64 v[142:143], v[238:239], 0, s[90:91]
	s_addc_u32 s31, s35, 0
	s_add_i32 s34, s60, s4
	global_load_lds_dwordx4 v[142:143], off
	v_lshl_add_u64 v[142:143], s[30:31], 0, v[128:129]
	s_mov_b32 m0, s34
	s_nop 0
	global_load_lds_dwordx4 v[142:143], off
	v_lshl_add_u64 v[142:143], s[30:31], 0, v[130:131]
	s_add_i32 m0, s34, 0x2000
	s_nop 0
	global_load_lds_dwordx4 v[142:143], off
	v_lshl_add_u64 v[142:143], v[240:241], 0, s[90:91]
	s_mov_b32 m0, s21
	s_nop 0
	global_load_lds_dwordx4 v[142:143], off
	v_lshl_add_u64 v[142:143], v[242:243], 0, s[90:91]
	s_mov_b32 m0, s48
	s_nop 0
	global_load_lds_dwordx4 v[142:143], off
	s_waitcnt vmcnt(8)
	s_waitcnt lgkmcnt(0)
	s_barrier
	s_setprio 1
	s_waitcnt lgkmcnt(0)
	v_mfma_f32_16x16x32_bf16 v[52:55], v[146:149], v[198:201], v[52:55]
	v_mfma_f32_16x16x32_bf16 v[60:63], v[154:157], v[198:201], v[60:63]
	v_mfma_f32_16x16x32_bf16 v[28:31], v[146:149], v[206:209], v[28:31]
	v_mfma_f32_16x16x32_bf16 v[36:39], v[154:157], v[206:209], v[36:39]
	v_mfma_f32_16x16x32_bf16 v[12:15], v[146:149], v[214:217], v[12:15]
	v_mfma_f32_16x16x32_bf16 v[16:19], v[154:157], v[214:217], v[16:19]
	v_mfma_f32_16x16x32_bf16 v[0:3], v[146:149], v[222:225], v[0:3]
	v_mfma_f32_16x16x32_bf16 v[4:7], v[154:157], v[222:225], v[4:7]
	v_mfma_f32_16x16x32_bf16 v[52:55], v[150:153], v[202:205], v[52:55]
	v_mfma_f32_16x16x32_bf16 v[60:63], v[158:161], v[202:205], v[60:63]
	v_mfma_f32_16x16x32_bf16 v[28:31], v[150:153], v[210:213], v[28:31]
	v_mfma_f32_16x16x32_bf16 v[36:39], v[158:161], v[210:213], v[36:39]
	v_mfma_f32_16x16x32_bf16 v[12:15], v[150:153], v[218:221], v[12:15]
	v_mfma_f32_16x16x32_bf16 v[16:19], v[158:161], v[218:221], v[16:19]
	v_mfma_f32_16x16x32_bf16 v[0:3], v[150:153], v[226:229], v[0:3]
	v_mfma_f32_16x16x32_bf16 v[4:7], v[158:161], v[226:229], v[4:7]
	v_mfma_f32_16x16x32_bf16 v[80:83], v[162:165], v[198:201], v[80:83]
	v_mfma_f32_16x16x32_bf16 v[84:87], v[170:173], v[198:201], v[84:87]
	v_mfma_f32_16x16x32_bf16 v[48:51], v[162:165], v[206:209], v[48:51]
	v_mfma_f32_16x16x32_bf16 v[56:59], v[170:173], v[206:209], v[56:59]
	v_mfma_f32_16x16x32_bf16 v[24:27], v[162:165], v[214:217], v[24:27]
	v_mfma_f32_16x16x32_bf16 v[32:35], v[170:173], v[214:217], v[32:35]
	v_mfma_f32_16x16x32_bf16 v[8:11], v[162:165], v[222:225], v[8:11]
	v_mfma_f32_16x16x32_bf16 v[20:23], v[170:173], v[222:225], v[20:23]
	v_mfma_f32_16x16x32_bf16 v[80:83], v[166:169], v[202:205], v[80:83]
	v_mfma_f32_16x16x32_bf16 v[84:87], v[174:177], v[202:205], v[84:87]
	v_mfma_f32_16x16x32_bf16 v[48:51], v[166:169], v[210:213], v[48:51]
	v_mfma_f32_16x16x32_bf16 v[56:59], v[174:177], v[210:213], v[56:59]
	v_mfma_f32_16x16x32_bf16 v[24:27], v[166:169], v[218:221], v[24:27]
	v_mfma_f32_16x16x32_bf16 v[32:35], v[174:177], v[218:221], v[32:35]
	v_mfma_f32_16x16x32_bf16 v[8:11], v[166:169], v[226:229], v[8:11]
	v_mfma_f32_16x16x32_bf16 v[20:23], v[174:177], v[226:229], v[20:23]
	s_setprio 0
	s_barrier
	s_add_i32 s58, s58, 2
	s_add_u32 s56, s56, 0x100
	s_addc_u32 s57, s57, 0
	s_add_u32 s28, s28, 0x100
	s_addc_u32 s29, s29, 0
	s_cmp_gt_u32 s58, 13
	s_cbranch_scc0 .LBB0_273
	s_and_b64 vcc, exec, s[16:17]
	s_cbranch_vccz .LBB0_276
	s_barrier

.LBB0_296:
	s_add_u32 s8, s10, 0x100
	s_addc_u32 s9, s11, 0
	s_add_i32 s30, 0, 0x10000
	s_cmp_eq_u32 s55, 2
	s_cselect_b32 s37, s27, s9
	s_cselect_b32 s36, s26, s8
	v_add_u32_e32 v138, s30, v141
	s_cselect_b32 s35, s29, s53
	s_cselect_b32 s34, s28, s52
	s_add_i32 s31, 0, 0x14000
	ds_read_b128 v[148:151], v138
	ds_read_b128 v[152:155], v138 offset:1024
	ds_read_b128 v[156:159], v138 offset:2048
	ds_read_b128 v[160:163], v138 offset:3072
	v_add_u32_e32 v138, s31, v141
	ds_read_b128 v[164:167], v138
	ds_read_b128 v[168:171], v138 offset:1024
	ds_read_b128 v[172:175], v138 offset:2048
	ds_read_b128 v[198:201], v138 offset:3072
	v_lshl_add_u64 v[138:139], s[10:11], 0, v[136:137]
	s_add_i32 m0, s39, 0xc000
	ds_read_b128 v[202:205], v145
	ds_read_b128 v[206:209], v145 offset:1024
	ds_read_b128 v[210:213], v145 offset:2048
	ds_read_b128 v[214:217], v145 offset:3072
	ds_read_b128 v[218:221], v145 offset:4096
	ds_read_b128 v[222:225], v145 offset:5120
	ds_read_b128 v[226:229], v145 offset:6144
	ds_read_b128 v[238:241], v145 offset:7168
	global_load_lds_dwordx4 v[138:139], off
	v_lshl_add_u64 v[138:139], s[10:11], 0, v[134:135]
	s_add_i32 m0, s39, 0xe000
	s_nop 0
	global_load_lds_dwordx4 v[138:139], off
	s_waitcnt vmcnt(8)
	s_waitcnt lgkmcnt(0)
	s_barrier
	s_setprio 1
	s_waitcnt lgkmcnt(0)
	v_mfma_f32_16x16x32_bf16 v[124:127], v[148:151], v[202:205], v[124:127]
	v_mfma_f32_16x16x32_bf16 v[120:123], v[156:159], v[202:205], v[120:123]
	v_mfma_f32_16x16x32_bf16 v[116:119], v[148:151], v[210:213], v[116:119]
	v_mfma_f32_16x16x32_bf16 v[112:115], v[156:159], v[210:213], v[112:115]
	v_mfma_f32_16x16x32_bf16 v[108:111], v[148:151], v[218:221], v[108:111]
	v_mfma_f32_16x16x32_bf16 v[104:107], v[156:159], v[218:221], v[104:107]
	v_mfma_f32_16x16x32_bf16 v[100:103], v[148:151], v[226:229], v[100:103]
	v_mfma_f32_16x16x32_bf16 v[96:99], v[156:159], v[226:229], v[96:99]
	v_mfma_f32_16x16x32_bf16 v[124:127], v[152:155], v[206:209], v[124:127]
	v_mfma_f32_16x16x32_bf16 v[120:123], v[160:163], v[206:209], v[120:123]
	v_mfma_f32_16x16x32_bf16 v[116:119], v[152:155], v[214:217], v[116:119]
	v_mfma_f32_16x16x32_bf16 v[112:115], v[160:163], v[214:217], v[112:115]
	v_mfma_f32_16x16x32_bf16 v[108:111], v[152:155], v[222:225], v[108:111]
	v_mfma_f32_16x16x32_bf16 v[104:107], v[160:163], v[222:225], v[104:107]
	v_mfma_f32_16x16x32_bf16 v[100:103], v[152:155], v[238:241], v[100:103]
	v_mfma_f32_16x16x32_bf16 v[96:99], v[160:163], v[238:241], v[96:99]
	v_mfma_f32_16x16x32_bf16 v[60:63], v[164:167], v[202:205], v[60:63]
	v_mfma_f32_16x16x32_bf16 v[56:59], v[172:175], v[202:205], v[56:59]
	v_mfma_f32_16x16x32_bf16 v[52:55], v[164:167], v[210:213], v[52:55]
	v_mfma_f32_16x16x32_bf16 v[48:51], v[172:175], v[210:213], v[48:51]
	v_mfma_f32_16x16x32_bf16 v[44:47], v[164:167], v[218:221], v[44:47]
	v_mfma_f32_16x16x32_bf16 v[40:43], v[172:175], v[218:221], v[40:43]
	v_mfma_f32_16x16x32_bf16 v[36:39], v[164:167], v[226:229], v[36:39]
	v_mfma_f32_16x16x32_bf16 v[32:35], v[172:175], v[226:229], v[32:35]
	v_mfma_f32_16x16x32_bf16 v[60:63], v[168:171], v[206:209], v[60:63]
	v_mfma_f32_16x16x32_bf16 v[56:59], v[198:201], v[206:209], v[56:59]
	v_mfma_f32_16x16x32_bf16 v[52:55], v[168:171], v[214:217], v[52:55]
	v_mfma_f32_16x16x32_bf16 v[48:51], v[198:201], v[214:217], v[48:51]
	v_mfma_f32_16x16x32_bf16 v[44:47], v[168:171], v[222:225], v[44:47]
	v_mfma_f32_16x16x32_bf16 v[40:43], v[198:201], v[222:225], v[40:43]
	v_mfma_f32_16x16x32_bf16 v[36:39], v[168:171], v[238:241], v[36:39]
	v_mfma_f32_16x16x32_bf16 v[32:35], v[198:201], v[238:241], v[32:35]
	s_setprio 0
	s_barrier
	s_add_i32 s10, s30, s38
	v_lshl_add_u64 v[138:139], s[34:35], 0, v[130:131]
	s_mov_b32 m0, s10
	ds_read_b128 v[202:205], v145 offset:16384
	ds_read_b128 v[206:209], v145 offset:17408
	ds_read_b128 v[210:213], v145 offset:18432
	ds_read_b128 v[214:217], v145 offset:19456
	ds_read_b128 v[218:221], v145 offset:20480
	ds_read_b128 v[222:225], v145 offset:21504
	ds_read_b128 v[226:229], v145 offset:22528
	ds_read_b128 v[238:241], v145 offset:23552
	global_load_lds_dwordx4 v[138:139], off
	s_add_i32 m0, s10, 0x2000
	s_add_u32 s10, s34, 0x18000
	v_lshl_add_u64 v[176:177], s[34:35], 0, v[132:133]
	s_addc_u32 s11, s35, 0
	s_add_i32 s30, s31, s38
	global_load_lds_dwordx4 v[176:177], off
	v_lshl_add_u64 v[242:243], s[10:11], 0, v[130:131]
	s_mov_b32 m0, s30
	v_lshl_add_u64 v[244:245], s[36:37], 0, v[132:133]
	global_load_lds_dwordx4 v[242:243], off
	v_lshl_add_u64 v[242:243], s[10:11], 0, v[132:133]
	s_add_i32 m0, s30, 0x2000
	s_nop 0
	global_load_lds_dwordx4 v[242:243], off
	v_lshl_add_u64 v[242:243], s[36:37], 0, v[130:131]
	s_mov_b32 m0, s39
	s_nop 0
	global_load_lds_dwordx4 v[242:243], off
	s_mov_b32 m0, s40
	s_nop 0
	global_load_lds_dwordx4 v[244:245], off
	s_waitcnt vmcnt(8)
	s_waitcnt lgkmcnt(0)
	s_barrier
	s_setprio 1
	s_waitcnt lgkmcnt(0)
	v_mfma_f32_16x16x32_bf16 v[92:95], v[148:151], v[202:205], v[92:95]
	v_mfma_f32_16x16x32_bf16 v[88:91], v[156:159], v[202:205], v[88:91]
	v_mfma_f32_16x16x32_bf16 v[84:87], v[148:151], v[210:213], v[84:87]
	v_mfma_f32_16x16x32_bf16 v[80:83], v[156:159], v[210:213], v[80:83]
	v_mfma_f32_16x16x32_bf16 v[76:79], v[148:151], v[218:221], v[76:79]
	v_mfma_f32_16x16x32_bf16 v[72:75], v[156:159], v[218:221], v[72:75]
	v_mfma_f32_16x16x32_bf16 v[68:71], v[148:151], v[226:229], v[68:71]
	v_mfma_f32_16x16x32_bf16 v[64:67], v[156:159], v[226:229], v[64:67]
	v_mfma_f32_16x16x32_bf16 v[92:95], v[152:155], v[206:209], v[92:95]
	v_mfma_f32_16x16x32_bf16 v[88:91], v[160:163], v[206:209], v[88:91]
	v_mfma_f32_16x16x32_bf16 v[84:87], v[152:155], v[214:217], v[84:87]
	v_mfma_f32_16x16x32_bf16 v[80:83], v[160:163], v[214:217], v[80:83]
	v_mfma_f32_16x16x32_bf16 v[76:79], v[152:155], v[222:225], v[76:79]
	v_mfma_f32_16x16x32_bf16 v[72:75], v[160:163], v[222:225], v[72:75]
	v_mfma_f32_16x16x32_bf16 v[68:71], v[152:155], v[238:241], v[68:71]
	v_mfma_f32_16x16x32_bf16 v[64:67], v[160:163], v[238:241], v[64:67]
	v_mfma_f32_16x16x32_bf16 v[28:31], v[164:167], v[202:205], v[28:31]
	v_mfma_f32_16x16x32_bf16 v[24:27], v[172:175], v[202:205], v[24:27]
	v_mfma_f32_16x16x32_bf16 v[20:23], v[164:167], v[210:213], v[20:23]
	v_mfma_f32_16x16x32_bf16 v[16:19], v[172:175], v[210:213], v[16:19]
	v_mfma_f32_16x16x32_bf16 v[12:15], v[164:167], v[218:221], v[12:15]
	v_mfma_f32_16x16x32_bf16 v[8:11], v[172:175], v[218:221], v[8:11]
	v_mfma_f32_16x16x32_bf16 v[4:7], v[164:167], v[226:229], v[4:7]
	v_mfma_f32_16x16x32_bf16 v[0:3], v[172:175], v[226:229], v[0:3]
	v_mfma_f32_16x16x32_bf16 v[28:31], v[168:171], v[206:209], v[28:31]
	v_mfma_f32_16x16x32_bf16 v[24:27], v[198:201], v[206:209], v[24:27]
	v_mfma_f32_16x16x32_bf16 v[20:23], v[168:171], v[214:217], v[20:23]
	v_mfma_f32_16x16x32_bf16 v[16:19], v[198:201], v[214:217], v[16:19]
	v_mfma_f32_16x16x32_bf16 v[12:15], v[168:171], v[222:225], v[12:15]
	v_mfma_f32_16x16x32_bf16 v[8:11], v[198:201], v[222:225], v[8:11]
	v_mfma_f32_16x16x32_bf16 v[4:7], v[168:171], v[238:241], v[4:7]
	v_mfma_f32_16x16x32_bf16 v[0:3], v[198:201], v[238:241], v[0:3]
	s_setprio 0
	s_barrier
	s_add_i32 s30, 0, 0x18000
	v_add_u32_e32 v147, s30, v141
	s_add_i32 s31, 0, 0x1c000
	ds_read_b128 v[148:151], v147
	ds_read_b128 v[152:155], v147 offset:1024
	ds_read_b128 v[156:159], v147 offset:2048
	ds_read_b128 v[160:163], v147 offset:3072
	v_add_u32_e32 v147, s31, v141
	ds_read_b128 v[164:167], v147
	ds_read_b128 v[168:171], v147 offset:1024
	ds_read_b128 v[172:175], v147 offset:2048
	ds_read_b128 v[198:201], v147 offset:3072
	s_add_u32 s10, s36, 0x18000
	s_addc_u32 s11, s37, 0
	s_mov_b32 m0, s41
	v_lshl_add_u64 v[246:247], s[10:11], 0, v[130:131]
	ds_read_b128 v[202:205], v145 offset:32768
	ds_read_b128 v[206:209], v145 offset:33792
	ds_read_b128 v[210:213], v145 offset:34816
	ds_read_b128 v[214:217], v145 offset:35840
	ds_read_b128 v[218:221], v145 offset:36864
	ds_read_b128 v[222:225], v145 offset:37888
	ds_read_b128 v[226:229], v145 offset:38912
	ds_read_b128 v[238:241], v145 offset:39936
	global_load_lds_dwordx4 v[246:247], off
	v_lshl_add_u64 v[246:247], s[10:11], 0, v[132:133]
	s_mov_b32 m0, s42
	s_nop 0
	global_load_lds_dwordx4 v[246:247], off
	s_waitcnt vmcnt(8)
	s_waitcnt lgkmcnt(0)
	s_barrier
	s_setprio 1
	s_waitcnt lgkmcnt(0)
	v_mfma_f32_16x16x32_bf16 v[124:127], v[148:151], v[202:205], v[124:127]
	v_mfma_f32_16x16x32_bf16 v[120:123], v[156:159], v[202:205], v[120:123]
	v_mfma_f32_16x16x32_bf16 v[116:119], v[148:151], v[210:213], v[116:119]
	v_mfma_f32_16x16x32_bf16 v[112:115], v[156:159], v[210:213], v[112:115]
	v_mfma_f32_16x16x32_bf16 v[108:111], v[148:151], v[218:221], v[108:111]
	v_mfma_f32_16x16x32_bf16 v[104:107], v[156:159], v[218:221], v[104:107]
	v_mfma_f32_16x16x32_bf16 v[100:103], v[148:151], v[226:229], v[100:103]
	v_mfma_f32_16x16x32_bf16 v[96:99], v[156:159], v[226:229], v[96:99]
	v_mfma_f32_16x16x32_bf16 v[124:127], v[152:155], v[206:209], v[124:127]
	v_mfma_f32_16x16x32_bf16 v[120:123], v[160:163], v[206:209], v[120:123]
	v_mfma_f32_16x16x32_bf16 v[116:119], v[152:155], v[214:217], v[116:119]
	v_mfma_f32_16x16x32_bf16 v[112:115], v[160:163], v[214:217], v[112:115]
	v_mfma_f32_16x16x32_bf16 v[108:111], v[152:155], v[222:225], v[108:111]
	v_mfma_f32_16x16x32_bf16 v[104:107], v[160:163], v[222:225], v[104:107]
	v_mfma_f32_16x16x32_bf16 v[100:103], v[152:155], v[238:241], v[100:103]
	v_mfma_f32_16x16x32_bf16 v[96:99], v[160:163], v[238:241], v[96:99]
	v_mfma_f32_16x16x32_bf16 v[60:63], v[164:167], v[202:205], v[60:63]
	v_mfma_f32_16x16x32_bf16 v[56:59], v[172:175], v[202:205], v[56:59]
	v_mfma_f32_16x16x32_bf16 v[52:55], v[164:167], v[210:213], v[52:55]
	v_mfma_f32_16x16x32_bf16 v[48:51], v[172:175], v[210:213], v[48:51]
	v_mfma_f32_16x16x32_bf16 v[44:47], v[164:167], v[218:221], v[44:47]
	v_mfma_f32_16x16x32_bf16 v[40:43], v[172:175], v[218:221], v[40:43]
	v_mfma_f32_16x16x32_bf16 v[36:39], v[164:167], v[226:229], v[36:39]
	v_mfma_f32_16x16x32_bf16 v[32:35], v[172:175], v[226:229], v[32:35]
	v_mfma_f32_16x16x32_bf16 v[60:63], v[168:171], v[206:209], v[60:63]
	v_mfma_f32_16x16x32_bf16 v[56:59], v[198:201], v[206:209], v[56:59]
	v_mfma_f32_16x16x32_bf16 v[52:55], v[168:171], v[214:217], v[52:55]
	v_mfma_f32_16x16x32_bf16 v[48:51], v[198:201], v[214:217], v[48:51]
	v_mfma_f32_16x16x32_bf16 v[44:47], v[168:171], v[222:225], v[44:47]
	v_mfma_f32_16x16x32_bf16 v[40:43], v[198:201], v[222:225], v[40:43]
	v_mfma_f32_16x16x32_bf16 v[36:39], v[168:171], v[238:241], v[36:39]
	v_mfma_f32_16x16x32_bf16 v[32:35], v[198:201], v[238:241], v[32:35]
	s_setprio 0
	s_barrier
	s_add_i32 s10, s30, s38
	v_lshl_add_u64 v[138:139], v[138:139], 0, s[90:91]
	s_mov_b32 m0, s10
	ds_read_b128 v[202:205], v145 offset:49152
	ds_read_b128 v[206:209], v145 offset:50176
	ds_read_b128 v[210:213], v145 offset:51200
	ds_read_b128 v[214:217], v145 offset:52224
	ds_read_b128 v[218:221], v145 offset:53248
	ds_read_b128 v[222:225], v145 offset:54272
	ds_read_b128 v[226:229], v145 offset:55296
	ds_read_b128 v[238:241], v145 offset:56320
	global_load_lds_dwordx4 v[138:139], off
	s_add_i32 m0, s10, 0x2000
	s_add_u32 s10, s34, 0x18080
	v_lshl_add_u64 v[138:139], v[176:177], 0, s[90:91]
	s_addc_u32 s11, s35, 0
	s_add_i32 s30, s31, s38
	global_load_lds_dwordx4 v[138:139], off
	v_lshl_add_u64 v[138:139], s[10:11], 0, v[130:131]
	s_mov_b32 m0, s30
	s_nop 0
	global_load_lds_dwordx4 v[138:139], off
	v_lshl_add_u64 v[138:139], s[10:11], 0, v[132:133]
	s_add_i32 m0, s30, 0x2000
	s_nop 0
	global_load_lds_dwordx4 v[138:139], off
	v_lshl_add_u64 v[138:139], v[242:243], 0, s[90:91]
	s_mov_b32 m0, s45
	s_nop 0
	global_load_lds_dwordx4 v[138:139], off
	v_lshl_add_u64 v[138:139], v[244:245], 0, s[90:91]
	s_mov_b32 m0, s46
	s_nop 0
	global_load_lds_dwordx4 v[138:139], off
	s_waitcnt vmcnt(8)
	s_waitcnt lgkmcnt(0)
	s_barrier
	s_setprio 1
	s_waitcnt lgkmcnt(0)
	v_mfma_f32_16x16x32_bf16 v[92:95], v[148:151], v[202:205], v[92:95]
	v_mfma_f32_16x16x32_bf16 v[88:91], v[156:159], v[202:205], v[88:91]
	v_mfma_f32_16x16x32_bf16 v[84:87], v[148:151], v[210:213], v[84:87]
	v_mfma_f32_16x16x32_bf16 v[80:83], v[156:159], v[210:213], v[80:83]
	v_mfma_f32_16x16x32_bf16 v[76:79], v[148:151], v[218:221], v[76:79]
	v_mfma_f32_16x16x32_bf16 v[72:75], v[156:159], v[218:221], v[72:75]
	v_mfma_f32_16x16x32_bf16 v[68:71], v[148:151], v[226:229], v[68:71]
	v_mfma_f32_16x16x32_bf16 v[64:67], v[156:159], v[226:229], v[64:67]
	v_mfma_f32_16x16x32_bf16 v[92:95], v[152:155], v[206:209], v[92:95]
	v_mfma_f32_16x16x32_bf16 v[88:91], v[160:163], v[206:209], v[88:91]
	v_mfma_f32_16x16x32_bf16 v[84:87], v[152:155], v[214:217], v[84:87]
	v_mfma_f32_16x16x32_bf16 v[80:83], v[160:163], v[214:217], v[80:83]
	v_mfma_f32_16x16x32_bf16 v[76:79], v[152:155], v[222:225], v[76:79]
	v_mfma_f32_16x16x32_bf16 v[72:75], v[160:163], v[222:225], v[72:75]
	v_mfma_f32_16x16x32_bf16 v[68:71], v[152:155], v[238:241], v[68:71]
	v_mfma_f32_16x16x32_bf16 v[64:67], v[160:163], v[238:241], v[64:67]
	v_mfma_f32_16x16x32_bf16 v[28:31], v[164:167], v[202:205], v[28:31]
	v_mfma_f32_16x16x32_bf16 v[24:27], v[172:175], v[202:205], v[24:27]
	v_mfma_f32_16x16x32_bf16 v[20:23], v[164:167], v[210:213], v[20:23]
	v_mfma_f32_16x16x32_bf16 v[16:19], v[172:175], v[210:213], v[16:19]
	v_mfma_f32_16x16x32_bf16 v[12:15], v[164:167], v[218:221], v[12:15]
	v_mfma_f32_16x16x32_bf16 v[8:11], v[172:175], v[218:221], v[8:11]
	v_mfma_f32_16x16x32_bf16 v[4:7], v[164:167], v[226:229], v[4:7]
	v_mfma_f32_16x16x32_bf16 v[0:3], v[172:175], v[226:229], v[0:3]
	v_mfma_f32_16x16x32_bf16 v[28:31], v[168:171], v[206:209], v[28:31]
	v_mfma_f32_16x16x32_bf16 v[24:27], v[198:201], v[206:209], v[24:27]
	v_mfma_f32_16x16x32_bf16 v[20:23], v[168:171], v[214:217], v[20:23]
	v_mfma_f32_16x16x32_bf16 v[16:19], v[198:201], v[214:217], v[16:19]
	v_mfma_f32_16x16x32_bf16 v[12:15], v[168:171], v[222:225], v[12:15]
	v_mfma_f32_16x16x32_bf16 v[8:11], v[198:201], v[222:225], v[8:11]
	v_mfma_f32_16x16x32_bf16 v[4:7], v[168:171], v[238:241], v[4:7]
	v_mfma_f32_16x16x32_bf16 v[0:3], v[198:201], v[238:241], v[0:3]
	s_setprio 0
	s_barrier
	s_add_i32 s55, s55, 2
	s_add_u32 s52, s52, 0x100
	s_addc_u32 s53, s53, 0
	s_cmp_gt_u32 s55, 3
	s_mov_b64 s[10:11], s[8:9]
	s_cbranch_scc0 .LBB0_296
	s_and_b64 vcc, exec, s[24:25]
	s_cbranch_vccz .LBB0_299
	s_barrier

.LBB0_344:
	s_add_u32 s47, s34, s46
	s_addc_u32 s59, s35, 0
	s_add_u32 s48, s47, 0x100
	s_addc_u32 s49, s59, 0
	s_and_b64 s[30:31], s[44:45], exec
	s_cselect_b32 s49, s19, s49
	s_cselect_b32 s48, s57, s48
	s_add_u32 s30, s36, s46
	s_addc_u32 s31, s37, 0
	s_add_u32 s46, s30, 0x100
	s_addc_u32 s50, s31, 0
	s_add_i32 s74, 0, 0x10000
	s_and_b64 s[30:31], s[44:45], exec
	s_cselect_b32 s51, s17, s50
	s_cselect_b32 s50, s58, s46
	s_add_i32 s45, 0, 0x14000
	s_add_u32 s30, s47, 0x10080
	s_addc_u32 s31, s59, 0
	s_add_i32 s83, s74, s40
	s_add_i32 m0, s20, 0xc000
	s_add_i32 s82, s20, 0xe000
	s_add_i32 s84, s83, 0x2000
	s_add_u32 s60, s50, 0x10000
	v_add_u32_e32 v152, s74, v137
	v_add_u32_e32 v168, s45, v137
	s_addc_u32 s61, s51, 0
	s_add_i32 s85, s45, s40
	ds_read_b128 v[140:143], v152
	ds_read_b128 v[144:147], v152 offset:1024
	ds_read_b128 v[148:151], v152 offset:2048
	ds_read_b128 v[152:155], v152 offset:3072
	ds_read_b128 v[156:159], v168
	ds_read_b128 v[160:163], v168 offset:1024
	ds_read_b128 v[164:167], v168 offset:2048
	ds_read_b128 v[168:171], v168 offset:3072
	s_add_i32 s86, s85, 0x2000
	s_add_i32 s87, 0, 0x18000
	s_add_i32 s88, 0, 0x1c000
	s_add_u32 s46, s48, 0x10000
	s_addc_u32 s47, s49, 0
	s_add_i32 s73, s87, s40
	s_add_i32 s59, s73, 0x2000
	s_add_u32 s44, s50, 0x10080
	s_addc_u32 s45, s51, 0
	s_add_i32 s81, s88, s40
	s_add_i32 s74, s81, 0x2000
	v_lshl_add_u64 v[176:177], s[30:31], 0, v[134:135]
	ds_read_b128 v[172:175], v139
	ds_read_b128 v[198:201], v139 offset:1024
	ds_read_b128 v[202:205], v139 offset:2048
	ds_read_b128 v[206:209], v139 offset:3072
	ds_read_b128 v[210:213], v139 offset:4096
	ds_read_b128 v[214:217], v139 offset:5120
	ds_read_b128 v[218:221], v139 offset:6144
	ds_read_b128 v[222:225], v139 offset:7168
	global_load_lds_dwordx4 v[176:177], off
	v_lshl_add_u64 v[176:177], s[30:31], 0, v[132:133]
	s_mov_b32 m0, s82
	s_nop 0
	global_load_lds_dwordx4 v[176:177], off
	s_waitcnt vmcnt(8)
	s_waitcnt lgkmcnt(0)
	s_barrier
	s_setprio 1
	s_waitcnt lgkmcnt(0)
	v_mfma_f32_16x16x32_bf16 v[112:115], v[140:143], v[172:175], v[112:115]
	v_mfma_f32_16x16x32_bf16 v[116:119], v[148:151], v[172:175], v[116:119]
	v_mfma_f32_16x16x32_bf16 v[96:99], v[140:143], v[202:205], v[96:99]
	v_mfma_f32_16x16x32_bf16 v[100:103], v[148:151], v[202:205], v[100:103]
	v_mfma_f32_16x16x32_bf16 v[72:75], v[140:143], v[210:213], v[72:75]
	v_mfma_f32_16x16x32_bf16 v[80:83], v[148:151], v[210:213], v[80:83]
	v_mfma_f32_16x16x32_bf16 v[40:43], v[140:143], v[218:221], v[40:43]
	v_mfma_f32_16x16x32_bf16 v[48:51], v[148:151], v[218:221], v[48:51]
	v_mfma_f32_16x16x32_bf16 v[112:115], v[144:147], v[198:201], v[112:115]
	v_mfma_f32_16x16x32_bf16 v[116:119], v[152:155], v[198:201], v[116:119]
	v_mfma_f32_16x16x32_bf16 v[96:99], v[144:147], v[206:209], v[96:99]
	v_mfma_f32_16x16x32_bf16 v[100:103], v[152:155], v[206:209], v[100:103]
	v_mfma_f32_16x16x32_bf16 v[72:75], v[144:147], v[214:217], v[72:75]
	v_mfma_f32_16x16x32_bf16 v[80:83], v[152:155], v[214:217], v[80:83]
	v_mfma_f32_16x16x32_bf16 v[40:43], v[144:147], v[222:225], v[40:43]
	v_mfma_f32_16x16x32_bf16 v[48:51], v[152:155], v[222:225], v[48:51]
	v_mfma_f32_16x16x32_bf16 v[120:123], v[156:159], v[172:175], v[120:123]
	v_mfma_f32_16x16x32_bf16 v[124:127], v[164:167], v[172:175], v[124:127]
	v_mfma_f32_16x16x32_bf16 v[104:107], v[156:159], v[202:205], v[104:107]
	v_mfma_f32_16x16x32_bf16 v[108:111], v[164:167], v[202:205], v[108:111]
	v_mfma_f32_16x16x32_bf16 v[88:91], v[156:159], v[210:213], v[88:91]
	v_mfma_f32_16x16x32_bf16 v[92:95], v[164:167], v[210:213], v[92:95]
	v_mfma_f32_16x16x32_bf16 v[64:67], v[156:159], v[218:221], v[64:67]
	v_mfma_f32_16x16x32_bf16 v[68:71], v[164:167], v[218:221], v[68:71]
	v_mfma_f32_16x16x32_bf16 v[120:123], v[160:163], v[198:201], v[120:123]
	v_mfma_f32_16x16x32_bf16 v[124:127], v[168:171], v[198:201], v[124:127]
	v_mfma_f32_16x16x32_bf16 v[104:107], v[160:163], v[206:209], v[104:107]
	v_mfma_f32_16x16x32_bf16 v[108:111], v[168:171], v[206:209], v[108:111]
	v_mfma_f32_16x16x32_bf16 v[88:91], v[160:163], v[214:217], v[88:91]
	v_mfma_f32_16x16x32_bf16 v[92:95], v[168:171], v[214:217], v[92:95]
	v_mfma_f32_16x16x32_bf16 v[64:67], v[160:163], v[222:225], v[64:67]
	v_mfma_f32_16x16x32_bf16 v[68:71], v[168:171], v[222:225], v[68:71]
	s_setprio 0
	s_barrier
	s_mov_b32 m0, s83
	v_lshl_add_u64 v[176:177], s[50:51], 0, v[128:129]
	ds_read_b128 v[172:175], v139 offset:16384
	ds_read_b128 v[198:201], v139 offset:17408
	ds_read_b128 v[202:205], v139 offset:18432
	ds_read_b128 v[206:209], v139 offset:19456
	ds_read_b128 v[210:213], v139 offset:20480
	ds_read_b128 v[214:217], v139 offset:21504
	ds_read_b128 v[218:221], v139 offset:22528
	ds_read_b128 v[222:225], v139 offset:23552
	global_load_lds_dwordx4 v[176:177], off
	v_lshl_add_u64 v[226:227], s[50:51], 0, v[130:131]
	s_mov_b32 m0, s84
	v_lshl_add_u64 v[228:229], s[60:61], 0, v[128:129]
	global_load_lds_dwordx4 v[226:227], off
	s_mov_b32 m0, s85
	v_lshl_add_u64 v[238:239], s[48:49], 0, v[132:133]
	global_load_lds_dwordx4 v[228:229], off
	v_lshl_add_u64 v[228:229], s[60:61], 0, v[130:131]
	s_mov_b32 m0, s86
	s_nop 0
	global_load_lds_dwordx4 v[228:229], off
	v_lshl_add_u64 v[228:229], s[48:49], 0, v[134:135]
	s_mov_b32 m0, s20
	s_nop 0
	global_load_lds_dwordx4 v[228:229], off
	s_mov_b32 m0, s21
	s_nop 0
	global_load_lds_dwordx4 v[238:239], off
	s_waitcnt vmcnt(8)
	s_waitcnt lgkmcnt(0)
	s_barrier
	s_setprio 1
	s_waitcnt lgkmcnt(0)
	v_mfma_f32_16x16x32_bf16 v[56:59], v[140:143], v[172:175], v[56:59]
	v_mfma_f32_16x16x32_bf16 v[60:63], v[148:151], v[172:175], v[60:63]
	v_mfma_f32_16x16x32_bf16 v[32:35], v[140:143], v[202:205], v[32:35]
	v_mfma_f32_16x16x32_bf16 v[36:39], v[148:151], v[202:205], v[36:39]
	v_mfma_f32_16x16x32_bf16 v[16:19], v[140:143], v[210:213], v[16:19]
	v_mfma_f32_16x16x32_bf16 v[20:23], v[148:151], v[210:213], v[20:23]
	v_mfma_f32_16x16x32_bf16 v[0:3], v[140:143], v[218:221], v[0:3]
	v_mfma_f32_16x16x32_bf16 v[4:7], v[148:151], v[218:221], v[4:7]
	v_mfma_f32_16x16x32_bf16 v[56:59], v[144:147], v[198:201], v[56:59]
	v_mfma_f32_16x16x32_bf16 v[60:63], v[152:155], v[198:201], v[60:63]
	v_mfma_f32_16x16x32_bf16 v[32:35], v[144:147], v[206:209], v[32:35]
	v_mfma_f32_16x16x32_bf16 v[36:39], v[152:155], v[206:209], v[36:39]
	v_mfma_f32_16x16x32_bf16 v[16:19], v[144:147], v[214:217], v[16:19]
	v_mfma_f32_16x16x32_bf16 v[20:23], v[152:155], v[214:217], v[20:23]
	v_mfma_f32_16x16x32_bf16 v[0:3], v[144:147], v[222:225], v[0:3]
	v_mfma_f32_16x16x32_bf16 v[4:7], v[152:155], v[222:225], v[4:7]
	v_mfma_f32_16x16x32_bf16 v[76:79], v[156:159], v[172:175], v[76:79]
	v_mfma_f32_16x16x32_bf16 v[84:87], v[164:167], v[172:175], v[84:87]
	v_mfma_f32_16x16x32_bf16 v[44:47], v[156:159], v[202:205], v[44:47]
	v_mfma_f32_16x16x32_bf16 v[52:55], v[164:167], v[202:205], v[52:55]
	v_mfma_f32_16x16x32_bf16 v[24:27], v[156:159], v[210:213], v[24:27]
	v_mfma_f32_16x16x32_bf16 v[28:31], v[164:167], v[210:213], v[28:31]
	v_mfma_f32_16x16x32_bf16 v[8:11], v[156:159], v[218:221], v[8:11]
	v_mfma_f32_16x16x32_bf16 v[12:15], v[164:167], v[218:221], v[12:15]
	v_mfma_f32_16x16x32_bf16 v[76:79], v[160:163], v[198:201], v[76:79]
	v_mfma_f32_16x16x32_bf16 v[84:87], v[168:171], v[198:201], v[84:87]
	v_mfma_f32_16x16x32_bf16 v[44:47], v[160:163], v[206:209], v[44:47]
	v_mfma_f32_16x16x32_bf16 v[52:55], v[168:171], v[206:209], v[52:55]
	v_mfma_f32_16x16x32_bf16 v[24:27], v[160:163], v[214:217], v[24:27]
	v_mfma_f32_16x16x32_bf16 v[28:31], v[168:171], v[214:217], v[28:31]
	v_mfma_f32_16x16x32_bf16 v[8:11], v[160:163], v[222:225], v[8:11]
	v_mfma_f32_16x16x32_bf16 v[12:15], v[168:171], v[222:225], v[12:15]
	s_setprio 0
	s_barrier
	v_add_u32_e32 v152, s87, v137
	v_add_u32_e32 v168, s88, v137
	ds_read_b128 v[140:143], v152
	ds_read_b128 v[144:147], v152 offset:1024
	ds_read_b128 v[148:151], v152 offset:2048
	ds_read_b128 v[152:155], v152 offset:3072
	ds_read_b128 v[156:159], v168
	ds_read_b128 v[160:163], v168 offset:1024
	ds_read_b128 v[164:167], v168 offset:2048
	ds_read_b128 v[168:171], v168 offset:3072
	s_mov_b32 m0, s25
	v_lshl_add_u64 v[240:241], s[46:47], 0, v[134:135]
	ds_read_b128 v[172:175], v139 offset:32768
	ds_read_b128 v[198:201], v139 offset:33792
	ds_read_b128 v[202:205], v139 offset:34816
	ds_read_b128 v[206:209], v139 offset:35840
	ds_read_b128 v[210:213], v139 offset:36864
	ds_read_b128 v[214:217], v139 offset:37888
	ds_read_b128 v[218:221], v139 offset:38912
	ds_read_b128 v[222:225], v139 offset:39936
	global_load_lds_dwordx4 v[240:241], off
	v_lshl_add_u64 v[240:241], s[46:47], 0, v[132:133]
	s_mov_b32 m0, s42
	s_nop 0
	global_load_lds_dwordx4 v[240:241], off
	s_waitcnt vmcnt(8)
	s_waitcnt lgkmcnt(0)
	s_barrier
	s_setprio 1
	s_waitcnt lgkmcnt(0)
	v_mfma_f32_16x16x32_bf16 v[112:115], v[140:143], v[172:175], v[112:115]
	v_mfma_f32_16x16x32_bf16 v[116:119], v[148:151], v[172:175], v[116:119]
	v_mfma_f32_16x16x32_bf16 v[96:99], v[140:143], v[202:205], v[96:99]
	v_mfma_f32_16x16x32_bf16 v[100:103], v[148:151], v[202:205], v[100:103]
	v_mfma_f32_16x16x32_bf16 v[72:75], v[140:143], v[210:213], v[72:75]
	v_mfma_f32_16x16x32_bf16 v[80:83], v[148:151], v[210:213], v[80:83]
	v_mfma_f32_16x16x32_bf16 v[40:43], v[140:143], v[218:221], v[40:43]
	v_mfma_f32_16x16x32_bf16 v[48:51], v[148:151], v[218:221], v[48:51]
	v_mfma_f32_16x16x32_bf16 v[112:115], v[144:147], v[198:201], v[112:115]
	v_mfma_f32_16x16x32_bf16 v[116:119], v[152:155], v[198:201], v[116:119]
	v_mfma_f32_16x16x32_bf16 v[96:99], v[144:147], v[206:209], v[96:99]
	v_mfma_f32_16x16x32_bf16 v[100:103], v[152:155], v[206:209], v[100:103]
	v_mfma_f32_16x16x32_bf16 v[72:75], v[144:147], v[214:217], v[72:75]
	v_mfma_f32_16x16x32_bf16 v[80:83], v[152:155], v[214:217], v[80:83]
	v_mfma_f32_16x16x32_bf16 v[40:43], v[144:147], v[222:225], v[40:43]
	v_mfma_f32_16x16x32_bf16 v[48:51], v[152:155], v[222:225], v[48:51]
	v_mfma_f32_16x16x32_bf16 v[120:123], v[156:159], v[172:175], v[120:123]
	v_mfma_f32_16x16x32_bf16 v[124:127], v[164:167], v[172:175], v[124:127]
	v_mfma_f32_16x16x32_bf16 v[104:107], v[156:159], v[202:205], v[104:107]
	v_mfma_f32_16x16x32_bf16 v[108:111], v[164:167], v[202:205], v[108:111]
	v_mfma_f32_16x16x32_bf16 v[88:91], v[156:159], v[210:213], v[88:91]
	v_mfma_f32_16x16x32_bf16 v[92:95], v[164:167], v[210:213], v[92:95]
	v_mfma_f32_16x16x32_bf16 v[64:67], v[156:159], v[218:221], v[64:67]
	v_mfma_f32_16x16x32_bf16 v[68:71], v[164:167], v[218:221], v[68:71]
	v_mfma_f32_16x16x32_bf16 v[120:123], v[160:163], v[198:201], v[120:123]
	v_mfma_f32_16x16x32_bf16 v[124:127], v[168:171], v[198:201], v[124:127]
	v_mfma_f32_16x16x32_bf16 v[104:107], v[160:163], v[206:209], v[104:107]
	v_mfma_f32_16x16x32_bf16 v[108:111], v[168:171], v[206:209], v[108:111]
	v_mfma_f32_16x16x32_bf16 v[88:91], v[160:163], v[214:217], v[88:91]
	v_mfma_f32_16x16x32_bf16 v[92:95], v[168:171], v[214:217], v[92:95]
	v_mfma_f32_16x16x32_bf16 v[64:67], v[160:163], v[222:225], v[64:67]
	v_mfma_f32_16x16x32_bf16 v[68:71], v[168:171], v[222:225], v[68:71]
	s_setprio 0
	s_barrier
	s_mov_b32 m0, s73
	v_lshl_add_u64 v[176:177], v[176:177], 0, s[90:91]
	ds_read_b128 v[172:175], v139 offset:49152
	ds_read_b128 v[198:201], v139 offset:50176
	ds_read_b128 v[202:205], v139 offset:51200
	ds_read_b128 v[206:209], v139 offset:52224
	ds_read_b128 v[210:213], v139 offset:53248
	ds_read_b128 v[214:217], v139 offset:54272
	ds_read_b128 v[218:221], v139 offset:55296
	ds_read_b128 v[222:225], v139 offset:56320
	global_load_lds_dwordx4 v[176:177], off
	v_lshl_add_u64 v[176:177], v[226:227], 0, s[90:91]
	s_mov_b32 m0, s59
	s_nop 0
	global_load_lds_dwordx4 v[176:177], off
	v_lshl_add_u64 v[176:177], s[44:45], 0, v[128:129]
	s_mov_b32 m0, s81
	s_nop 0
	global_load_lds_dwordx4 v[176:177], off
	v_lshl_add_u64 v[176:177], s[44:45], 0, v[130:131]
	s_mov_b32 m0, s74
	s_nop 0
	global_load_lds_dwordx4 v[176:177], off
	v_lshl_add_u64 v[176:177], v[228:229], 0, s[90:91]
	s_mov_b32 m0, s43
	s_nop 0
	global_load_lds_dwordx4 v[176:177], off
	v_lshl_add_u64 v[176:177], v[238:239], 0, s[90:91]
	s_mov_b32 m0, s52
	s_nop 0
	global_load_lds_dwordx4 v[176:177], off
	s_waitcnt vmcnt(8)
	s_waitcnt lgkmcnt(0)
	s_barrier
	s_setprio 1
	s_waitcnt lgkmcnt(0)
	v_mfma_f32_16x16x32_bf16 v[56:59], v[140:143], v[172:175], v[56:59]
	v_mfma_f32_16x16x32_bf16 v[60:63], v[148:151], v[172:175], v[60:63]
	v_mfma_f32_16x16x32_bf16 v[32:35], v[140:143], v[202:205], v[32:35]
	v_mfma_f32_16x16x32_bf16 v[36:39], v[148:151], v[202:205], v[36:39]
	v_mfma_f32_16x16x32_bf16 v[16:19], v[140:143], v[210:213], v[16:19]
	v_mfma_f32_16x16x32_bf16 v[20:23], v[148:151], v[210:213], v[20:23]
	v_mfma_f32_16x16x32_bf16 v[0:3], v[140:143], v[218:221], v[0:3]
	v_mfma_f32_16x16x32_bf16 v[4:7], v[148:151], v[218:221], v[4:7]
	v_mfma_f32_16x16x32_bf16 v[56:59], v[144:147], v[198:201], v[56:59]
	v_mfma_f32_16x16x32_bf16 v[60:63], v[152:155], v[198:201], v[60:63]
	v_mfma_f32_16x16x32_bf16 v[32:35], v[144:147], v[206:209], v[32:35]
	v_mfma_f32_16x16x32_bf16 v[36:39], v[152:155], v[206:209], v[36:39]
	v_mfma_f32_16x16x32_bf16 v[16:19], v[144:147], v[214:217], v[16:19]
	v_mfma_f32_16x16x32_bf16 v[20:23], v[152:155], v[214:217], v[20:23]
	v_mfma_f32_16x16x32_bf16 v[0:3], v[144:147], v[222:225], v[0:3]
	v_mfma_f32_16x16x32_bf16 v[4:7], v[152:155], v[222:225], v[4:7]
	v_mfma_f32_16x16x32_bf16 v[76:79], v[156:159], v[172:175], v[76:79]
	v_mfma_f32_16x16x32_bf16 v[84:87], v[164:167], v[172:175], v[84:87]
	v_mfma_f32_16x16x32_bf16 v[44:47], v[156:159], v[202:205], v[44:47]
	v_mfma_f32_16x16x32_bf16 v[52:55], v[164:167], v[202:205], v[52:55]
	v_mfma_f32_16x16x32_bf16 v[24:27], v[156:159], v[210:213], v[24:27]
	v_mfma_f32_16x16x32_bf16 v[28:31], v[164:167], v[210:213], v[28:31]
	v_mfma_f32_16x16x32_bf16 v[8:11], v[156:159], v[218:221], v[8:11]
	v_mfma_f32_16x16x32_bf16 v[12:15], v[164:167], v[218:221], v[12:15]
	v_mfma_f32_16x16x32_bf16 v[76:79], v[160:163], v[198:201], v[76:79]
	v_mfma_f32_16x16x32_bf16 v[84:87], v[168:171], v[198:201], v[84:87]
	v_mfma_f32_16x16x32_bf16 v[44:47], v[160:163], v[206:209], v[44:47]
	v_mfma_f32_16x16x32_bf16 v[52:55], v[168:171], v[206:209], v[52:55]
	v_mfma_f32_16x16x32_bf16 v[24:27], v[160:163], v[214:217], v[24:27]
	v_mfma_f32_16x16x32_bf16 v[28:31], v[168:171], v[214:217], v[28:31]
	v_mfma_f32_16x16x32_bf16 v[8:11], v[160:163], v[222:225], v[8:11]
	v_mfma_f32_16x16x32_bf16 v[12:15], v[168:171], v[222:225], v[12:15]
	s_setprio 0
	s_barrier
	s_movk_i32 s46, 0x100
	s_andn2_b64 vcc, exec, s[38:39]
	s_mov_b64 s[44:45], -1
	s_mov_b64 s[38:39], 0
	s_cbranch_vccz .LBB0_344
	s_and_b64 vcc, exec, s[14:15]
	s_cbranch_vccz .LBB0_347
	s_barrier

.LBB0_360:
	s_add_u32 s39, s18, s38
	s_addc_u32 s48, s19, 0
	s_add_u32 s44, s39, 0x100
	s_addc_u32 s45, s48, 0
	s_and_b64 s[30:31], s[36:37], exec
	s_cselect_b32 s45, s15, s45
	s_cselect_b32 s44, s55, s44
	s_add_u32 s30, s24, s38
	s_addc_u32 s31, s25, 0
	s_add_u32 s38, s30, 0x100
	s_addc_u32 s46, s31, 0
	s_add_i32 s59, 0, 0x10000
	s_and_b64 s[30:31], s[36:37], exec
	s_cselect_b32 s47, s13, s46
	s_cselect_b32 s46, s56, s38
	s_add_i32 s37, 0, 0x14000
	s_add_u32 s30, s39, 0x10080
	s_addc_u32 s31, s48, 0
	s_add_i32 s67, s59, s40
	s_add_i32 m0, s17, 0xc000
	s_add_i32 s61, s17, 0xe000
	s_add_i32 s73, s67, 0x2000
	s_add_u32 s48, s46, 0x10000
	v_add_u32_e32 v152, s59, v137
	v_add_u32_e32 v168, s37, v137
	s_addc_u32 s49, s47, 0
	s_add_i32 s74, s37, s40
	ds_read_b128 v[140:143], v152
	ds_read_b128 v[144:147], v152 offset:1024
	ds_read_b128 v[148:151], v152 offset:2048
	ds_read_b128 v[152:155], v152 offset:3072
	ds_read_b128 v[156:159], v168
	ds_read_b128 v[160:163], v168 offset:1024
	ds_read_b128 v[164:167], v168 offset:2048
	ds_read_b128 v[168:171], v168 offset:3072
	s_add_i32 s81, s74, 0x2000
	s_add_i32 s82, 0, 0x18000
	s_add_i32 s83, 0, 0x1c000
	s_add_u32 s38, s44, 0x10000
	s_addc_u32 s39, s45, 0
	s_add_i32 s58, s82, s40
	s_add_i32 s57, s58, 0x2000
	s_add_u32 s36, s46, 0x10080
	s_addc_u32 s37, s47, 0
	s_add_i32 s60, s83, s40
	s_add_i32 s59, s60, 0x2000
	v_lshl_add_u64 v[176:177], s[30:31], 0, v[134:135]
	ds_read_b128 v[172:175], v139
	ds_read_b128 v[198:201], v139 offset:1024
	ds_read_b128 v[202:205], v139 offset:2048
	ds_read_b128 v[206:209], v139 offset:3072
	ds_read_b128 v[210:213], v139 offset:4096
	ds_read_b128 v[214:217], v139 offset:5120
	ds_read_b128 v[218:221], v139 offset:6144
	ds_read_b128 v[222:225], v139 offset:7168
	global_load_lds_dwordx4 v[176:177], off
	v_lshl_add_u64 v[176:177], s[30:31], 0, v[132:133]
	s_mov_b32 m0, s61
	s_nop 0
	global_load_lds_dwordx4 v[176:177], off
	s_waitcnt vmcnt(8)
	s_waitcnt lgkmcnt(0)
	s_barrier
	s_setprio 1
	s_waitcnt lgkmcnt(0)
	v_mfma_f32_16x16x32_bf16 v[108:111], v[140:143], v[172:175], v[108:111]
	v_mfma_f32_16x16x32_bf16 v[116:119], v[148:151], v[172:175], v[116:119]
	v_mfma_f32_16x16x32_bf16 v[92:95], v[140:143], v[202:205], v[92:95]
	v_mfma_f32_16x16x32_bf16 v[100:103], v[148:151], v[202:205], v[100:103]
	v_mfma_f32_16x16x32_bf16 v[68:71], v[140:143], v[210:213], v[68:71]
	v_mfma_f32_16x16x32_bf16 v[76:79], v[148:151], v[210:213], v[76:79]
	v_mfma_f32_16x16x32_bf16 v[40:43], v[140:143], v[218:221], v[40:43]
	v_mfma_f32_16x16x32_bf16 v[44:47], v[148:151], v[218:221], v[44:47]
	v_mfma_f32_16x16x32_bf16 v[108:111], v[144:147], v[198:201], v[108:111]
	v_mfma_f32_16x16x32_bf16 v[116:119], v[152:155], v[198:201], v[116:119]
	v_mfma_f32_16x16x32_bf16 v[92:95], v[144:147], v[206:209], v[92:95]
	v_mfma_f32_16x16x32_bf16 v[100:103], v[152:155], v[206:209], v[100:103]
	v_mfma_f32_16x16x32_bf16 v[68:71], v[144:147], v[214:217], v[68:71]
	v_mfma_f32_16x16x32_bf16 v[76:79], v[152:155], v[214:217], v[76:79]
	v_mfma_f32_16x16x32_bf16 v[40:43], v[144:147], v[222:225], v[40:43]
	v_mfma_f32_16x16x32_bf16 v[44:47], v[152:155], v[222:225], v[44:47]
	v_mfma_f32_16x16x32_bf16 v[120:123], v[156:159], v[172:175], v[120:123]
	v_mfma_f32_16x16x32_bf16 v[124:127], v[164:167], v[172:175], v[124:127]
	v_mfma_f32_16x16x32_bf16 v[104:107], v[156:159], v[202:205], v[104:107]
	v_mfma_f32_16x16x32_bf16 v[112:115], v[164:167], v[202:205], v[112:115]
	v_mfma_f32_16x16x32_bf16 v[88:91], v[156:159], v[210:213], v[88:91]
	v_mfma_f32_16x16x32_bf16 v[96:99], v[164:167], v[210:213], v[96:99]
	v_mfma_f32_16x16x32_bf16 v[64:67], v[156:159], v[218:221], v[64:67]
	v_mfma_f32_16x16x32_bf16 v[72:75], v[164:167], v[218:221], v[72:75]
	v_mfma_f32_16x16x32_bf16 v[120:123], v[160:163], v[198:201], v[120:123]
	v_mfma_f32_16x16x32_bf16 v[124:127], v[168:171], v[198:201], v[124:127]
	v_mfma_f32_16x16x32_bf16 v[104:107], v[160:163], v[206:209], v[104:107]
	v_mfma_f32_16x16x32_bf16 v[112:115], v[168:171], v[206:209], v[112:115]
	v_mfma_f32_16x16x32_bf16 v[88:91], v[160:163], v[214:217], v[88:91]
	v_mfma_f32_16x16x32_bf16 v[96:99], v[168:171], v[214:217], v[96:99]
	v_mfma_f32_16x16x32_bf16 v[64:67], v[160:163], v[222:225], v[64:67]
	v_mfma_f32_16x16x32_bf16 v[72:75], v[168:171], v[222:225], v[72:75]
	s_setprio 0
	s_barrier
	s_mov_b32 m0, s67
	v_lshl_add_u64 v[176:177], s[46:47], 0, v[128:129]
	ds_read_b128 v[172:175], v139 offset:16384
	ds_read_b128 v[198:201], v139 offset:17408
	ds_read_b128 v[202:205], v139 offset:18432
	ds_read_b128 v[206:209], v139 offset:19456
	ds_read_b128 v[210:213], v139 offset:20480
	ds_read_b128 v[214:217], v139 offset:21504
	ds_read_b128 v[218:221], v139 offset:22528
	ds_read_b128 v[222:225], v139 offset:23552
	global_load_lds_dwordx4 v[176:177], off
	v_lshl_add_u64 v[226:227], s[46:47], 0, v[130:131]
	s_mov_b32 m0, s73
	v_lshl_add_u64 v[228:229], s[48:49], 0, v[128:129]
	global_load_lds_dwordx4 v[226:227], off
	s_mov_b32 m0, s74
	v_lshl_add_u64 v[238:239], s[44:45], 0, v[132:133]
	global_load_lds_dwordx4 v[228:229], off
	v_lshl_add_u64 v[228:229], s[48:49], 0, v[130:131]
	s_mov_b32 m0, s81
	s_nop 0
	global_load_lds_dwordx4 v[228:229], off
	v_lshl_add_u64 v[228:229], s[44:45], 0, v[134:135]
	s_mov_b32 m0, s17
	s_nop 0
	global_load_lds_dwordx4 v[228:229], off
	s_mov_b32 m0, s20
	s_nop 0
	global_load_lds_dwordx4 v[238:239], off
	s_waitcnt vmcnt(8)
	s_waitcnt lgkmcnt(0)
	s_barrier
	s_setprio 1
	s_waitcnt lgkmcnt(0)
	v_mfma_f32_16x16x32_bf16 v[52:55], v[140:143], v[172:175], v[52:55]
	v_mfma_f32_16x16x32_bf16 v[60:63], v[148:151], v[172:175], v[60:63]
	v_mfma_f32_16x16x32_bf16 v[28:31], v[140:143], v[202:205], v[28:31]
	v_mfma_f32_16x16x32_bf16 v[36:39], v[148:151], v[202:205], v[36:39]
	v_mfma_f32_16x16x32_bf16 v[12:15], v[140:143], v[210:213], v[12:15]
	v_mfma_f32_16x16x32_bf16 v[16:19], v[148:151], v[210:213], v[16:19]
	v_mfma_f32_16x16x32_bf16 v[0:3], v[140:143], v[218:221], v[0:3]
	v_mfma_f32_16x16x32_bf16 v[4:7], v[148:151], v[218:221], v[4:7]
	v_mfma_f32_16x16x32_bf16 v[52:55], v[144:147], v[198:201], v[52:55]
	v_mfma_f32_16x16x32_bf16 v[60:63], v[152:155], v[198:201], v[60:63]
	v_mfma_f32_16x16x32_bf16 v[28:31], v[144:147], v[206:209], v[28:31]
	v_mfma_f32_16x16x32_bf16 v[36:39], v[152:155], v[206:209], v[36:39]
	v_mfma_f32_16x16x32_bf16 v[12:15], v[144:147], v[214:217], v[12:15]
	v_mfma_f32_16x16x32_bf16 v[16:19], v[152:155], v[214:217], v[16:19]
	v_mfma_f32_16x16x32_bf16 v[0:3], v[144:147], v[222:225], v[0:3]
	v_mfma_f32_16x16x32_bf16 v[4:7], v[152:155], v[222:225], v[4:7]
	v_mfma_f32_16x16x32_bf16 v[80:83], v[156:159], v[172:175], v[80:83]
	v_mfma_f32_16x16x32_bf16 v[84:87], v[164:167], v[172:175], v[84:87]
	v_mfma_f32_16x16x32_bf16 v[48:51], v[156:159], v[202:205], v[48:51]
	v_mfma_f32_16x16x32_bf16 v[56:59], v[164:167], v[202:205], v[56:59]
	v_mfma_f32_16x16x32_bf16 v[24:27], v[156:159], v[210:213], v[24:27]
	v_mfma_f32_16x16x32_bf16 v[32:35], v[164:167], v[210:213], v[32:35]
	v_mfma_f32_16x16x32_bf16 v[8:11], v[156:159], v[218:221], v[8:11]
	v_mfma_f32_16x16x32_bf16 v[20:23], v[164:167], v[218:221], v[20:23]
	v_mfma_f32_16x16x32_bf16 v[80:83], v[160:163], v[198:201], v[80:83]
	v_mfma_f32_16x16x32_bf16 v[84:87], v[168:171], v[198:201], v[84:87]
	v_mfma_f32_16x16x32_bf16 v[48:51], v[160:163], v[206:209], v[48:51]
	v_mfma_f32_16x16x32_bf16 v[56:59], v[168:171], v[206:209], v[56:59]
	v_mfma_f32_16x16x32_bf16 v[24:27], v[160:163], v[214:217], v[24:27]
	v_mfma_f32_16x16x32_bf16 v[32:35], v[168:171], v[214:217], v[32:35]
	v_mfma_f32_16x16x32_bf16 v[8:11], v[160:163], v[222:225], v[8:11]
	v_mfma_f32_16x16x32_bf16 v[20:23], v[168:171], v[222:225], v[20:23]
	s_setprio 0
	s_barrier
	v_add_u32_e32 v152, s82, v137
	v_add_u32_e32 v168, s83, v137
	ds_read_b128 v[140:143], v152
	ds_read_b128 v[144:147], v152 offset:1024
	ds_read_b128 v[148:151], v152 offset:2048
	ds_read_b128 v[152:155], v152 offset:3072
	ds_read_b128 v[156:159], v168
	ds_read_b128 v[160:163], v168 offset:1024
	ds_read_b128 v[164:167], v168 offset:2048
	ds_read_b128 v[168:171], v168 offset:3072
	s_mov_b32 m0, s21
	v_lshl_add_u64 v[240:241], s[38:39], 0, v[134:135]
	ds_read_b128 v[172:175], v139 offset:32768
	ds_read_b128 v[198:201], v139 offset:33792
	ds_read_b128 v[202:205], v139 offset:34816
	ds_read_b128 v[206:209], v139 offset:35840
	ds_read_b128 v[210:213], v139 offset:36864
	ds_read_b128 v[214:217], v139 offset:37888
	ds_read_b128 v[218:221], v139 offset:38912
	ds_read_b128 v[222:225], v139 offset:39936
	global_load_lds_dwordx4 v[240:241], off
	v_lshl_add_u64 v[240:241], s[38:39], 0, v[132:133]
	s_mov_b32 m0, s42
	s_nop 0
	global_load_lds_dwordx4 v[240:241], off
	s_waitcnt vmcnt(8)
	s_waitcnt lgkmcnt(0)
	s_barrier
	s_setprio 1
	s_waitcnt lgkmcnt(0)
	v_mfma_f32_16x16x32_bf16 v[108:111], v[140:143], v[172:175], v[108:111]
	v_mfma_f32_16x16x32_bf16 v[116:119], v[148:151], v[172:175], v[116:119]
	v_mfma_f32_16x16x32_bf16 v[92:95], v[140:143], v[202:205], v[92:95]
	v_mfma_f32_16x16x32_bf16 v[100:103], v[148:151], v[202:205], v[100:103]
	v_mfma_f32_16x16x32_bf16 v[68:71], v[140:143], v[210:213], v[68:71]
	v_mfma_f32_16x16x32_bf16 v[76:79], v[148:151], v[210:213], v[76:79]
	v_mfma_f32_16x16x32_bf16 v[40:43], v[140:143], v[218:221], v[40:43]
	v_mfma_f32_16x16x32_bf16 v[44:47], v[148:151], v[218:221], v[44:47]
	v_mfma_f32_16x16x32_bf16 v[108:111], v[144:147], v[198:201], v[108:111]
	v_mfma_f32_16x16x32_bf16 v[116:119], v[152:155], v[198:201], v[116:119]
	v_mfma_f32_16x16x32_bf16 v[92:95], v[144:147], v[206:209], v[92:95]
	v_mfma_f32_16x16x32_bf16 v[100:103], v[152:155], v[206:209], v[100:103]
	v_mfma_f32_16x16x32_bf16 v[68:71], v[144:147], v[214:217], v[68:71]
	v_mfma_f32_16x16x32_bf16 v[76:79], v[152:155], v[214:217], v[76:79]
	v_mfma_f32_16x16x32_bf16 v[40:43], v[144:147], v[222:225], v[40:43]
	v_mfma_f32_16x16x32_bf16 v[44:47], v[152:155], v[222:225], v[44:47]
	v_mfma_f32_16x16x32_bf16 v[120:123], v[156:159], v[172:175], v[120:123]
	v_mfma_f32_16x16x32_bf16 v[124:127], v[164:167], v[172:175], v[124:127]
	v_mfma_f32_16x16x32_bf16 v[104:107], v[156:159], v[202:205], v[104:107]
	v_mfma_f32_16x16x32_bf16 v[112:115], v[164:167], v[202:205], v[112:115]
	v_mfma_f32_16x16x32_bf16 v[88:91], v[156:159], v[210:213], v[88:91]
	v_mfma_f32_16x16x32_bf16 v[96:99], v[164:167], v[210:213], v[96:99]
	v_mfma_f32_16x16x32_bf16 v[64:67], v[156:159], v[218:221], v[64:67]
	v_mfma_f32_16x16x32_bf16 v[72:75], v[164:167], v[218:221], v[72:75]
	v_mfma_f32_16x16x32_bf16 v[120:123], v[160:163], v[198:201], v[120:123]
	v_mfma_f32_16x16x32_bf16 v[124:127], v[168:171], v[198:201], v[124:127]
	v_mfma_f32_16x16x32_bf16 v[104:107], v[160:163], v[206:209], v[104:107]
	v_mfma_f32_16x16x32_bf16 v[112:115], v[168:171], v[206:209], v[112:115]
	v_mfma_f32_16x16x32_bf16 v[88:91], v[160:163], v[214:217], v[88:91]
	v_mfma_f32_16x16x32_bf16 v[96:99], v[168:171], v[214:217], v[96:99]
	v_mfma_f32_16x16x32_bf16 v[64:67], v[160:163], v[222:225], v[64:67]
	v_mfma_f32_16x16x32_bf16 v[72:75], v[168:171], v[222:225], v[72:75]
	s_setprio 0
	s_barrier
	s_mov_b32 m0, s58
	v_lshl_add_u64 v[176:177], v[176:177], 0, s[90:91]
	ds_read_b128 v[172:175], v139 offset:49152
	ds_read_b128 v[198:201], v139 offset:50176
	ds_read_b128 v[202:205], v139 offset:51200
	ds_read_b128 v[206:209], v139 offset:52224
	ds_read_b128 v[210:213], v139 offset:53248
	ds_read_b128 v[214:217], v139 offset:54272
	ds_read_b128 v[218:221], v139 offset:55296
	ds_read_b128 v[222:225], v139 offset:56320
	global_load_lds_dwordx4 v[176:177], off
	v_lshl_add_u64 v[176:177], v[226:227], 0, s[90:91]
	s_mov_b32 m0, s57
	s_nop 0
	global_load_lds_dwordx4 v[176:177], off
	v_lshl_add_u64 v[176:177], s[36:37], 0, v[128:129]
	s_mov_b32 m0, s60
	s_nop 0
	global_load_lds_dwordx4 v[176:177], off
	v_lshl_add_u64 v[176:177], s[36:37], 0, v[130:131]
	s_mov_b32 m0, s59
	s_nop 0
	global_load_lds_dwordx4 v[176:177], off
	v_lshl_add_u64 v[176:177], v[228:229], 0, s[90:91]
	s_mov_b32 m0, s43
	s_nop 0
	global_load_lds_dwordx4 v[176:177], off
	v_lshl_add_u64 v[176:177], v[238:239], 0, s[90:91]
	s_mov_b32 m0, s50
	s_nop 0
	global_load_lds_dwordx4 v[176:177], off
	s_waitcnt vmcnt(8)
	s_waitcnt lgkmcnt(0)
	s_barrier
	s_setprio 1
	s_waitcnt lgkmcnt(0)
	v_mfma_f32_16x16x32_bf16 v[52:55], v[140:143], v[172:175], v[52:55]
	v_mfma_f32_16x16x32_bf16 v[60:63], v[148:151], v[172:175], v[60:63]
	v_mfma_f32_16x16x32_bf16 v[28:31], v[140:143], v[202:205], v[28:31]
	v_mfma_f32_16x16x32_bf16 v[36:39], v[148:151], v[202:205], v[36:39]
	v_mfma_f32_16x16x32_bf16 v[12:15], v[140:143], v[210:213], v[12:15]
	v_mfma_f32_16x16x32_bf16 v[16:19], v[148:151], v[210:213], v[16:19]
	v_mfma_f32_16x16x32_bf16 v[0:3], v[140:143], v[218:221], v[0:3]
	v_mfma_f32_16x16x32_bf16 v[4:7], v[148:151], v[218:221], v[4:7]
	v_mfma_f32_16x16x32_bf16 v[52:55], v[144:147], v[198:201], v[52:55]
	v_mfma_f32_16x16x32_bf16 v[60:63], v[152:155], v[198:201], v[60:63]
	v_mfma_f32_16x16x32_bf16 v[28:31], v[144:147], v[206:209], v[28:31]
	v_mfma_f32_16x16x32_bf16 v[36:39], v[152:155], v[206:209], v[36:39]
	v_mfma_f32_16x16x32_bf16 v[12:15], v[144:147], v[214:217], v[12:15]
	v_mfma_f32_16x16x32_bf16 v[16:19], v[152:155], v[214:217], v[16:19]
	v_mfma_f32_16x16x32_bf16 v[0:3], v[144:147], v[222:225], v[0:3]
	v_mfma_f32_16x16x32_bf16 v[4:7], v[152:155], v[222:225], v[4:7]
	v_mfma_f32_16x16x32_bf16 v[80:83], v[156:159], v[172:175], v[80:83]
	v_mfma_f32_16x16x32_bf16 v[84:87], v[164:167], v[172:175], v[84:87]
	v_mfma_f32_16x16x32_bf16 v[48:51], v[156:159], v[202:205], v[48:51]
	v_mfma_f32_16x16x32_bf16 v[56:59], v[164:167], v[202:205], v[56:59]
	v_mfma_f32_16x16x32_bf16 v[24:27], v[156:159], v[210:213], v[24:27]
	v_mfma_f32_16x16x32_bf16 v[32:35], v[164:167], v[210:213], v[32:35]
	v_mfma_f32_16x16x32_bf16 v[8:11], v[156:159], v[218:221], v[8:11]
	v_mfma_f32_16x16x32_bf16 v[20:23], v[164:167], v[218:221], v[20:23]
	v_mfma_f32_16x16x32_bf16 v[80:83], v[160:163], v[198:201], v[80:83]
	v_mfma_f32_16x16x32_bf16 v[84:87], v[168:171], v[198:201], v[84:87]
	v_mfma_f32_16x16x32_bf16 v[48:51], v[160:163], v[206:209], v[48:51]
	v_mfma_f32_16x16x32_bf16 v[56:59], v[168:171], v[206:209], v[56:59]
	v_mfma_f32_16x16x32_bf16 v[24:27], v[160:163], v[214:217], v[24:27]
	v_mfma_f32_16x16x32_bf16 v[32:35], v[168:171], v[214:217], v[32:35]
	v_mfma_f32_16x16x32_bf16 v[8:11], v[160:163], v[222:225], v[8:11]
	v_mfma_f32_16x16x32_bf16 v[20:23], v[168:171], v[222:225], v[20:23]
	s_setprio 0
	s_barrier
	s_movk_i32 s38, 0x100
	s_andn2_b64 vcc, exec, s[34:35]
	s_mov_b64 s[36:37], -1
	s_mov_b64 s[34:35], 0
	s_cbranch_vccz .LBB0_360
	s_and_b64 vcc, exec, s[10:11]
	s_cbranch_vccz .LBB0_363
	s_barrier

.LBB0_395:
	s_add_u32 s16, s14, 0xfffc0080
	s_addc_u32 s17, s15, -1
	s_add_i32 s30, 0, 0x10000
	s_cmp_eq_u32 s48, 12
	s_cselect_b32 s27, s21, s17
	s_cselect_b32 s26, s44, s16
	v_add_u32_e32 v142, s30, v145
	s_cselect_b32 s17, s19, s47
	s_cselect_b32 s16, s45, s46
	s_add_i32 s49, 0, 0x14000
	ds_read_b128 v[146:149], v142
	ds_read_b128 v[150:153], v142 offset:1024
	ds_read_b128 v[154:157], v142 offset:2048
	ds_read_b128 v[158:161], v142 offset:3072
	v_add_u32_e32 v142, s49, v145
	ds_read_b128 v[162:165], v142
	ds_read_b128 v[166:169], v142 offset:1024
	ds_read_b128 v[170:173], v142 offset:2048
	ds_read_b128 v[174:177], v142 offset:3072
	v_lshl_add_u64 v[142:143], s[14:15], 0, v[138:139]
	s_add_i32 m0, s9, 0xc000
	ds_read_b128 v[198:201], v141
	ds_read_b128 v[202:205], v141 offset:1024
	ds_read_b128 v[206:209], v141 offset:2048
	ds_read_b128 v[210:213], v141 offset:3072
	ds_read_b128 v[214:217], v141 offset:4096
	ds_read_b128 v[218:221], v141 offset:5120
	ds_read_b128 v[222:225], v141 offset:6144
	ds_read_b128 v[226:229], v141 offset:7168
	global_load_lds_dwordx4 v[142:143], off
	v_lshl_add_u64 v[142:143], s[14:15], 0, v[136:137]
	s_add_i32 m0, s9, 0xe000
	s_nop 0
	global_load_lds_dwordx4 v[142:143], off
	s_waitcnt vmcnt(8)
	s_waitcnt lgkmcnt(0)
	s_barrier
	s_setprio 1
	s_waitcnt lgkmcnt(0)
	v_mfma_f32_16x16x32_bf16 v[20:23], v[146:149], v[198:201], v[20:23]
	v_mfma_f32_16x16x32_bf16 v[28:31], v[154:157], v[198:201], v[28:31]
	v_mfma_f32_16x16x32_bf16 v[12:15], v[146:149], v[206:209], v[12:15]
	v_mfma_f32_16x16x32_bf16 v[24:27], v[154:157], v[206:209], v[24:27]
	v_mfma_f32_16x16x32_bf16 v[4:7], v[146:149], v[214:217], v[4:7]
	v_mfma_f32_16x16x32_bf16 v[16:19], v[154:157], v[214:217], v[16:19]
	v_mfma_f32_16x16x32_bf16 v[0:3], v[146:149], v[222:225], v[0:3]
	v_mfma_f32_16x16x32_bf16 v[8:11], v[154:157], v[222:225], v[8:11]
	v_mfma_f32_16x16x32_bf16 v[20:23], v[150:153], v[202:205], v[20:23]
	v_mfma_f32_16x16x32_bf16 v[28:31], v[158:161], v[202:205], v[28:31]
	v_mfma_f32_16x16x32_bf16 v[12:15], v[150:153], v[210:213], v[12:15]
	v_mfma_f32_16x16x32_bf16 v[24:27], v[158:161], v[210:213], v[24:27]
	v_mfma_f32_16x16x32_bf16 v[4:7], v[150:153], v[218:221], v[4:7]
	v_mfma_f32_16x16x32_bf16 v[16:19], v[158:161], v[218:221], v[16:19]
	v_mfma_f32_16x16x32_bf16 v[0:3], v[150:153], v[226:229], v[0:3]
	v_mfma_f32_16x16x32_bf16 v[8:11], v[158:161], v[226:229], v[8:11]
	v_mfma_f32_16x16x32_bf16 v[84:87], v[162:165], v[198:201], v[84:87]
	v_mfma_f32_16x16x32_bf16 v[92:95], v[170:173], v[198:201], v[92:95]
	v_mfma_f32_16x16x32_bf16 v[72:75], v[162:165], v[206:209], v[72:75]
	v_mfma_f32_16x16x32_bf16 v[88:91], v[170:173], v[206:209], v[88:91]
	v_mfma_f32_16x16x32_bf16 v[60:63], v[162:165], v[214:217], v[60:63]
	v_mfma_f32_16x16x32_bf16 v[80:83], v[170:173], v[214:217], v[80:83]
	v_mfma_f32_16x16x32_bf16 v[48:51], v[162:165], v[222:225], v[48:51]
	v_mfma_f32_16x16x32_bf16 v[68:71], v[170:173], v[222:225], v[68:71]
	v_mfma_f32_16x16x32_bf16 v[84:87], v[166:169], v[202:205], v[84:87]
	v_mfma_f32_16x16x32_bf16 v[92:95], v[174:177], v[202:205], v[92:95]
	v_mfma_f32_16x16x32_bf16 v[72:75], v[166:169], v[210:213], v[72:75]
	v_mfma_f32_16x16x32_bf16 v[88:91], v[174:177], v[210:213], v[88:91]
	v_mfma_f32_16x16x32_bf16 v[60:63], v[166:169], v[218:221], v[60:63]
	v_mfma_f32_16x16x32_bf16 v[80:83], v[174:177], v[218:221], v[80:83]
	v_mfma_f32_16x16x32_bf16 v[48:51], v[166:169], v[226:229], v[48:51]
	v_mfma_f32_16x16x32_bf16 v[68:71], v[174:177], v[226:229], v[68:71]
	s_setprio 0
	s_barrier
	s_add_i32 s30, s30, s34
	v_lshl_add_u64 v[142:143], s[16:17], 0, v[128:129]
	s_mov_b32 m0, s30
	ds_read_b128 v[198:201], v141 offset:16384
	ds_read_b128 v[202:205], v141 offset:17408
	ds_read_b128 v[206:209], v141 offset:18432
	ds_read_b128 v[210:213], v141 offset:19456
	ds_read_b128 v[214:217], v141 offset:20480
	ds_read_b128 v[218:221], v141 offset:21504
	ds_read_b128 v[222:225], v141 offset:22528
	ds_read_b128 v[226:229], v141 offset:23552
	global_load_lds_dwordx4 v[142:143], off
	s_add_i32 m0, s30, 0x2000
	s_add_u32 s30, s16, 0x40000
	v_lshl_add_u64 v[238:239], s[16:17], 0, v[130:131]
	s_addc_u32 s31, s17, 0
	s_add_i32 s49, s49, s34
	global_load_lds_dwordx4 v[238:239], off
	v_lshl_add_u64 v[240:241], s[30:31], 0, v[128:129]
	s_mov_b32 m0, s49
	v_lshl_add_u64 v[242:243], s[26:27], 0, v[132:133]
	global_load_lds_dwordx4 v[240:241], off
	v_lshl_add_u64 v[240:241], s[30:31], 0, v[130:131]
	s_add_i32 m0, s49, 0x2000
	s_nop 0
	global_load_lds_dwordx4 v[240:241], off
	v_lshl_add_u64 v[240:241], s[26:27], 0, v[134:135]
	s_mov_b32 m0, s9
	s_nop 0
	global_load_lds_dwordx4 v[240:241], off
	s_mov_b32 m0, s36
	s_nop 0
	global_load_lds_dwordx4 v[242:243], off
	s_waitcnt vmcnt(8)
	s_waitcnt lgkmcnt(0)
	s_barrier
	s_setprio 1
	s_waitcnt lgkmcnt(0)
	v_mfma_f32_16x16x32_bf16 v[56:59], v[146:149], v[198:201], v[56:59]
	v_mfma_f32_16x16x32_bf16 v[76:79], v[154:157], v[198:201], v[76:79]
	v_mfma_f32_16x16x32_bf16 v[44:47], v[146:149], v[206:209], v[44:47]
	v_mfma_f32_16x16x32_bf16 v[64:67], v[154:157], v[206:209], v[64:67]
	v_mfma_f32_16x16x32_bf16 v[36:39], v[146:149], v[214:217], v[36:39]
	v_mfma_f32_16x16x32_bf16 v[52:55], v[154:157], v[214:217], v[52:55]
	v_mfma_f32_16x16x32_bf16 v[32:35], v[146:149], v[222:225], v[32:35]
	v_mfma_f32_16x16x32_bf16 v[40:43], v[154:157], v[222:225], v[40:43]
	v_mfma_f32_16x16x32_bf16 v[56:59], v[150:153], v[202:205], v[56:59]
	v_mfma_f32_16x16x32_bf16 v[76:79], v[158:161], v[202:205], v[76:79]
	v_mfma_f32_16x16x32_bf16 v[44:47], v[150:153], v[210:213], v[44:47]
	v_mfma_f32_16x16x32_bf16 v[64:67], v[158:161], v[210:213], v[64:67]
	v_mfma_f32_16x16x32_bf16 v[36:39], v[150:153], v[218:221], v[36:39]
	v_mfma_f32_16x16x32_bf16 v[52:55], v[158:161], v[218:221], v[52:55]
	v_mfma_f32_16x16x32_bf16 v[32:35], v[150:153], v[226:229], v[32:35]
	v_mfma_f32_16x16x32_bf16 v[40:43], v[158:161], v[226:229], v[40:43]
	v_mfma_f32_16x16x32_bf16 v[112:115], v[162:165], v[198:201], v[112:115]
	v_mfma_f32_16x16x32_bf16 v[120:123], v[170:173], v[198:201], v[120:123]
	v_mfma_f32_16x16x32_bf16 v[104:107], v[162:165], v[206:209], v[104:107]
	v_mfma_f32_16x16x32_bf16 v[116:119], v[170:173], v[206:209], v[116:119]
	v_mfma_f32_16x16x32_bf16 v[100:103], v[162:165], v[214:217], v[100:103]
	v_mfma_f32_16x16x32_bf16 v[108:111], v[170:173], v[214:217], v[108:111]
	v_mfma_f32_16x16x32_bf16 v[96:99], v[162:165], v[222:225], v[96:99]
	v_mfma_f32_16x16x32_bf16 v[124:127], v[170:173], v[222:225], v[124:127]
	v_mfma_f32_16x16x32_bf16 v[112:115], v[166:169], v[202:205], v[112:115]
	v_mfma_f32_16x16x32_bf16 v[120:123], v[174:177], v[202:205], v[120:123]
	v_mfma_f32_16x16x32_bf16 v[104:107], v[166:169], v[210:213], v[104:107]
	v_mfma_f32_16x16x32_bf16 v[116:119], v[174:177], v[210:213], v[116:119]
	v_mfma_f32_16x16x32_bf16 v[100:103], v[166:169], v[218:221], v[100:103]
	v_mfma_f32_16x16x32_bf16 v[108:111], v[174:177], v[218:221], v[108:111]
	v_mfma_f32_16x16x32_bf16 v[96:99], v[166:169], v[226:229], v[96:99]
	v_mfma_f32_16x16x32_bf16 v[124:127], v[174:177], v[226:229], v[124:127]
	s_setprio 0
	s_barrier
	s_add_i32 s30, 0, 0x18000
	s_add_i32 s31, 0, 0x1c000
	v_add_u32_e32 v158, s30, v145
	v_add_u32_e32 v174, s31, v145
	ds_read_b128 v[146:149], v158
	ds_read_b128 v[150:153], v158 offset:1024
	ds_read_b128 v[154:157], v158 offset:2048
	ds_read_b128 v[158:161], v158 offset:3072
	ds_read_b128 v[162:165], v174
	ds_read_b128 v[166:169], v174 offset:1024
	ds_read_b128 v[170:173], v174 offset:2048
	ds_read_b128 v[174:177], v174 offset:3072
	s_add_u32 s26, s26, 0x40000
	s_addc_u32 s27, s27, 0
	s_mov_b32 m0, s37
	v_lshl_add_u64 v[244:245], s[26:27], 0, v[134:135]
	ds_read_b128 v[198:201], v141 offset:32768
	ds_read_b128 v[202:205], v141 offset:33792
	ds_read_b128 v[206:209], v141 offset:34816
	ds_read_b128 v[210:213], v141 offset:35840
	ds_read_b128 v[214:217], v141 offset:36864
	ds_read_b128 v[218:221], v141 offset:37888
	ds_read_b128 v[222:225], v141 offset:38912
	ds_read_b128 v[226:229], v141 offset:39936
	global_load_lds_dwordx4 v[244:245], off
	v_lshl_add_u64 v[244:245], s[26:27], 0, v[132:133]
	s_mov_b32 m0, s38
	s_nop 0
	global_load_lds_dwordx4 v[244:245], off
	s_waitcnt vmcnt(8)
	s_waitcnt lgkmcnt(0)
	s_barrier
	s_setprio 1
	s_waitcnt lgkmcnt(0)
	v_mfma_f32_16x16x32_bf16 v[20:23], v[146:149], v[198:201], v[20:23]
	v_mfma_f32_16x16x32_bf16 v[28:31], v[154:157], v[198:201], v[28:31]
	v_mfma_f32_16x16x32_bf16 v[12:15], v[146:149], v[206:209], v[12:15]
	v_mfma_f32_16x16x32_bf16 v[24:27], v[154:157], v[206:209], v[24:27]
	v_mfma_f32_16x16x32_bf16 v[4:7], v[146:149], v[214:217], v[4:7]
	v_mfma_f32_16x16x32_bf16 v[16:19], v[154:157], v[214:217], v[16:19]
	v_mfma_f32_16x16x32_bf16 v[0:3], v[146:149], v[222:225], v[0:3]
	v_mfma_f32_16x16x32_bf16 v[8:11], v[154:157], v[222:225], v[8:11]
	v_mfma_f32_16x16x32_bf16 v[20:23], v[150:153], v[202:205], v[20:23]
	v_mfma_f32_16x16x32_bf16 v[28:31], v[158:161], v[202:205], v[28:31]
	v_mfma_f32_16x16x32_bf16 v[12:15], v[150:153], v[210:213], v[12:15]
	v_mfma_f32_16x16x32_bf16 v[24:27], v[158:161], v[210:213], v[24:27]
	v_mfma_f32_16x16x32_bf16 v[4:7], v[150:153], v[218:221], v[4:7]
	v_mfma_f32_16x16x32_bf16 v[16:19], v[158:161], v[218:221], v[16:19]
	v_mfma_f32_16x16x32_bf16 v[0:3], v[150:153], v[226:229], v[0:3]
	v_mfma_f32_16x16x32_bf16 v[8:11], v[158:161], v[226:229], v[8:11]
	v_mfma_f32_16x16x32_bf16 v[84:87], v[162:165], v[198:201], v[84:87]
	v_mfma_f32_16x16x32_bf16 v[92:95], v[170:173], v[198:201], v[92:95]
	v_mfma_f32_16x16x32_bf16 v[72:75], v[162:165], v[206:209], v[72:75]
	v_mfma_f32_16x16x32_bf16 v[88:91], v[170:173], v[206:209], v[88:91]
	v_mfma_f32_16x16x32_bf16 v[60:63], v[162:165], v[214:217], v[60:63]
	v_mfma_f32_16x16x32_bf16 v[80:83], v[170:173], v[214:217], v[80:83]
	v_mfma_f32_16x16x32_bf16 v[48:51], v[162:165], v[222:225], v[48:51]
	v_mfma_f32_16x16x32_bf16 v[68:71], v[170:173], v[222:225], v[68:71]
	v_mfma_f32_16x16x32_bf16 v[84:87], v[166:169], v[202:205], v[84:87]
	v_mfma_f32_16x16x32_bf16 v[92:95], v[174:177], v[202:205], v[92:95]
	v_mfma_f32_16x16x32_bf16 v[72:75], v[166:169], v[210:213], v[72:75]
	v_mfma_f32_16x16x32_bf16 v[88:91], v[174:177], v[210:213], v[88:91]
	v_mfma_f32_16x16x32_bf16 v[60:63], v[166:169], v[218:221], v[60:63]
	v_mfma_f32_16x16x32_bf16 v[80:83], v[174:177], v[218:221], v[80:83]
	v_mfma_f32_16x16x32_bf16 v[48:51], v[166:169], v[226:229], v[48:51]
	v_mfma_f32_16x16x32_bf16 v[68:71], v[174:177], v[226:229], v[68:71]
	s_setprio 0
	s_barrier
	s_add_i32 s26, s30, s34
	v_lshl_add_u64 v[142:143], v[142:143], 0, s[90:91]
	s_mov_b32 m0, s26
	ds_read_b128 v[198:201], v141 offset:49152
	ds_read_b128 v[202:205], v141 offset:50176
	ds_read_b128 v[206:209], v141 offset:51200
	ds_read_b128 v[210:213], v141 offset:52224
	ds_read_b128 v[214:217], v141 offset:53248
	ds_read_b128 v[218:221], v141 offset:54272
	ds_read_b128 v[222:225], v141 offset:55296
	ds_read_b128 v[226:229], v141 offset:56320
	global_load_lds_dwordx4 v[142:143], off
	s_add_i32 m0, s26, 0x2000
	s_add_u32 s16, s16, 0x40080
	v_lshl_add_u64 v[142:143], v[238:239], 0, s[90:91]
	s_addc_u32 s17, s17, 0
	s_add_i32 s26, s31, s34
	global_load_lds_dwordx4 v[142:143], off
	v_lshl_add_u64 v[142:143], s[16:17], 0, v[128:129]
	s_mov_b32 m0, s26
	s_nop 0
	global_load_lds_dwordx4 v[142:143], off
	v_lshl_add_u64 v[142:143], s[16:17], 0, v[130:131]
	s_add_i32 m0, s26, 0x2000
	s_nop 0
	global_load_lds_dwordx4 v[142:143], off
	v_lshl_add_u64 v[142:143], v[240:241], 0, s[90:91]
	s_mov_b32 m0, s40
	s_nop 0
	global_load_lds_dwordx4 v[142:143], off
	v_lshl_add_u64 v[142:143], v[242:243], 0, s[90:91]
	s_mov_b32 m0, s41
	s_nop 0
	global_load_lds_dwordx4 v[142:143], off
	s_waitcnt vmcnt(8)
	s_waitcnt lgkmcnt(0)
	s_barrier
	s_setprio 1
	s_waitcnt lgkmcnt(0)
	v_mfma_f32_16x16x32_bf16 v[56:59], v[146:149], v[198:201], v[56:59]
	v_mfma_f32_16x16x32_bf16 v[76:79], v[154:157], v[198:201], v[76:79]
	v_mfma_f32_16x16x32_bf16 v[44:47], v[146:149], v[206:209], v[44:47]
	v_mfma_f32_16x16x32_bf16 v[64:67], v[154:157], v[206:209], v[64:67]
	v_mfma_f32_16x16x32_bf16 v[36:39], v[146:149], v[214:217], v[36:39]
	v_mfma_f32_16x16x32_bf16 v[52:55], v[154:157], v[214:217], v[52:55]
	v_mfma_f32_16x16x32_bf16 v[32:35], v[146:149], v[222:225], v[32:35]
	v_mfma_f32_16x16x32_bf16 v[40:43], v[154:157], v[222:225], v[40:43]
	v_mfma_f32_16x16x32_bf16 v[56:59], v[150:153], v[202:205], v[56:59]
	v_mfma_f32_16x16x32_bf16 v[76:79], v[158:161], v[202:205], v[76:79]
	v_mfma_f32_16x16x32_bf16 v[44:47], v[150:153], v[210:213], v[44:47]
	v_mfma_f32_16x16x32_bf16 v[64:67], v[158:161], v[210:213], v[64:67]
	v_mfma_f32_16x16x32_bf16 v[36:39], v[150:153], v[218:221], v[36:39]
	v_mfma_f32_16x16x32_bf16 v[52:55], v[158:161], v[218:221], v[52:55]
	v_mfma_f32_16x16x32_bf16 v[32:35], v[150:153], v[226:229], v[32:35]
	v_mfma_f32_16x16x32_bf16 v[40:43], v[158:161], v[226:229], v[40:43]
	v_mfma_f32_16x16x32_bf16 v[112:115], v[162:165], v[198:201], v[112:115]
	v_mfma_f32_16x16x32_bf16 v[120:123], v[170:173], v[198:201], v[120:123]
	v_mfma_f32_16x16x32_bf16 v[104:107], v[162:165], v[206:209], v[104:107]
	v_mfma_f32_16x16x32_bf16 v[116:119], v[170:173], v[206:209], v[116:119]
	v_mfma_f32_16x16x32_bf16 v[100:103], v[162:165], v[214:217], v[100:103]
	v_mfma_f32_16x16x32_bf16 v[108:111], v[170:173], v[214:217], v[108:111]
	v_mfma_f32_16x16x32_bf16 v[96:99], v[162:165], v[222:225], v[96:99]
	v_mfma_f32_16x16x32_bf16 v[124:127], v[170:173], v[222:225], v[124:127]
	v_mfma_f32_16x16x32_bf16 v[112:115], v[166:169], v[202:205], v[112:115]
	v_mfma_f32_16x16x32_bf16 v[120:123], v[174:177], v[202:205], v[120:123]
	v_mfma_f32_16x16x32_bf16 v[104:107], v[166:169], v[210:213], v[104:107]
	v_mfma_f32_16x16x32_bf16 v[116:119], v[174:177], v[210:213], v[116:119]
	v_mfma_f32_16x16x32_bf16 v[100:103], v[166:169], v[218:221], v[100:103]
	v_mfma_f32_16x16x32_bf16 v[108:111], v[174:177], v[218:221], v[108:111]
	v_mfma_f32_16x16x32_bf16 v[96:99], v[166:169], v[226:229], v[96:99]
	v_mfma_f32_16x16x32_bf16 v[124:127], v[174:177], v[226:229], v[124:127]
	s_setprio 0
	s_barrier
	s_add_i32 s48, s48, 2
	s_add_u32 s46, s46, 0x100
	s_addc_u32 s47, s47, 0
	s_add_u32 s14, s14, 0x100
	s_addc_u32 s15, s15, 0
	s_cmp_gt_u32 s48, 13
	s_cbranch_scc0 .LBB0_395
	s_and_b64 vcc, exec, s[12:13]
	s_cbranch_vccz .LBB0_398
	s_barrier

.LBB0_451:
	s_add_i32 s60, s50, 2
	s_add_u32 s30, s8, 0x80
	s_addc_u32 s31, s9, 0
	s_add_i32 s61, 0, 0x10000
	s_cmp_eq_u32 s21, s50
	s_cselect_b32 s51, s47, s31
	s_cselect_b32 s50, s46, s30
	v_add_u32_e32 v128, s61, v173
	s_cselect_b32 s31, s49, vcc_lo
	s_cselect_b32 s30, s48, s45
	s_add_i32 vcc_hi, 0, 0x14000
	ds_read_b128 v[130:133], v128
	ds_read_b128 v[134:137], v128 offset:1024
	ds_read_b128 v[138:141], v128 offset:2048
	ds_read_b128 v[142:145], v128 offset:3072
	v_add_u32_e32 v128, vcc_hi, v173
	ds_read_b128 v[158:161], v128
	ds_read_b128 v[162:165], v128 offset:1024
	ds_read_b128 v[166:169], v128 offset:2048
	ds_read_b128 v[198:201], v128 offset:3072
	v_lshl_add_u64 v[170:171], s[8:9], 0, v[156:157]
	s_add_i32 m0, s85, 0xc000
	ds_read_b128 v[202:205], v190
	ds_read_b128 v[206:209], v190 offset:1024
	ds_read_b128 v[210:213], v190 offset:2048
	ds_read_b128 v[214:217], v190 offset:3072
	ds_read_b128 v[218:221], v190 offset:4096
	ds_read_b128 v[222:225], v190 offset:5120
	ds_read_b128 v[226:229], v190 offset:6144
	ds_read_b128 v[238:241], v190 offset:7168
	global_load_lds_dwordx4 v[170:171], off
	v_lshl_add_u64 v[170:171], s[8:9], 0, v[154:155]
	s_add_i32 m0, s85, 0xe000
	s_nop 0
	global_load_lds_dwordx4 v[170:171], off
	s_waitcnt vmcnt(8)
	s_waitcnt lgkmcnt(0)
	s_barrier
	s_setprio 1
	s_waitcnt lgkmcnt(0)
	v_mfma_f32_16x16x32_bf16 v[124:127], v[130:133], v[202:205], v[124:127]
	v_mfma_f32_16x16x32_bf16 v[120:123], v[138:141], v[202:205], v[120:123]
	v_mfma_f32_16x16x32_bf16 v[108:111], v[130:133], v[210:213], v[108:111]
	v_mfma_f32_16x16x32_bf16 v[104:107], v[138:141], v[210:213], v[104:107]
	v_mfma_f32_16x16x32_bf16 v[92:95], v[130:133], v[218:221], v[92:95]
	v_mfma_f32_16x16x32_bf16 v[88:91], v[138:141], v[218:221], v[88:91]
	v_mfma_f32_16x16x32_bf16 v[76:79], v[130:133], v[226:229], v[76:79]
	v_mfma_f32_16x16x32_bf16 v[72:75], v[138:141], v[226:229], v[72:75]
	v_mfma_f32_16x16x32_bf16 v[124:127], v[134:137], v[206:209], v[124:127]
	v_mfma_f32_16x16x32_bf16 v[120:123], v[142:145], v[206:209], v[120:123]
	v_mfma_f32_16x16x32_bf16 v[108:111], v[134:137], v[214:217], v[108:111]
	v_mfma_f32_16x16x32_bf16 v[104:107], v[142:145], v[214:217], v[104:107]
	v_mfma_f32_16x16x32_bf16 v[92:95], v[134:137], v[222:225], v[92:95]
	v_mfma_f32_16x16x32_bf16 v[88:91], v[142:145], v[222:225], v[88:91]
	v_mfma_f32_16x16x32_bf16 v[76:79], v[134:137], v[238:241], v[76:79]
	v_mfma_f32_16x16x32_bf16 v[72:75], v[142:145], v[238:241], v[72:75]
	v_mfma_f32_16x16x32_bf16 v[116:119], v[158:161], v[202:205], v[116:119]
	v_mfma_f32_16x16x32_bf16 v[112:115], v[166:169], v[202:205], v[112:115]
	v_mfma_f32_16x16x32_bf16 v[100:103], v[158:161], v[210:213], v[100:103]
	v_mfma_f32_16x16x32_bf16 v[96:99], v[166:169], v[210:213], v[96:99]
	v_mfma_f32_16x16x32_bf16 v[84:87], v[158:161], v[218:221], v[84:87]
	v_mfma_f32_16x16x32_bf16 v[80:83], v[166:169], v[218:221], v[80:83]
	v_mfma_f32_16x16x32_bf16 v[68:71], v[158:161], v[226:229], v[68:71]
	v_mfma_f32_16x16x32_bf16 v[64:67], v[166:169], v[226:229], v[64:67]
	v_mfma_f32_16x16x32_bf16 v[116:119], v[162:165], v[206:209], v[116:119]
	v_mfma_f32_16x16x32_bf16 v[112:115], v[198:201], v[206:209], v[112:115]
	v_mfma_f32_16x16x32_bf16 v[100:103], v[162:165], v[214:217], v[100:103]
	v_mfma_f32_16x16x32_bf16 v[96:99], v[198:201], v[214:217], v[96:99]
	v_mfma_f32_16x16x32_bf16 v[84:87], v[162:165], v[222:225], v[84:87]
	v_mfma_f32_16x16x32_bf16 v[80:83], v[198:201], v[222:225], v[80:83]
	v_mfma_f32_16x16x32_bf16 v[68:71], v[162:165], v[238:241], v[68:71]
	v_mfma_f32_16x16x32_bf16 v[64:67], v[198:201], v[238:241], v[64:67]
	s_setprio 0
	s_barrier
	s_add_i32 s61, s61, s82
	v_lshl_add_u64 v[170:171], s[30:31], 0, v[148:149]
	s_mov_b32 m0, s61
	ds_read_b128 v[202:205], v190 offset:16384
	ds_read_b128 v[206:209], v190 offset:17408
	ds_read_b128 v[210:213], v190 offset:18432
	ds_read_b128 v[214:217], v190 offset:19456
	ds_read_b128 v[218:221], v190 offset:20480
	ds_read_b128 v[222:225], v190 offset:21504
	ds_read_b128 v[226:229], v190 offset:22528
	ds_read_b128 v[238:241], v190 offset:23552
	global_load_lds_dwordx4 v[170:171], off
	s_add_i32 m0, s61, 0x2000
	v_lshl_add_u64 v[242:243], s[30:31], 0, v[152:153]
	s_add_u32 s30, s30, s96
	s_addc_u32 s31, s31, 0
	s_add_i32 s61, vcc_hi, s82
	global_load_lds_dwordx4 v[242:243], off
	v_lshl_add_u64 v[244:245], s[30:31], 0, v[148:149]
	s_mov_b32 m0, s61
	v_lshl_add_u64 v[246:247], s[30:31], 0, v[152:153]
	global_load_lds_dwordx4 v[244:245], off
	s_add_i32 m0, s61, 0x2000
	v_lshl_add_u64 v[248:249], s[50:51], 0, v[146:147]
	global_load_lds_dwordx4 v[246:247], off
	s_mov_b32 m0, s85
	v_lshl_add_u64 v[250:251], s[50:51], 0, v[150:151]
	global_load_lds_dwordx4 v[248:249], off
	s_mov_b32 m0, s86
	s_nop 0
	global_load_lds_dwordx4 v[250:251], off
	s_waitcnt vmcnt(8)
	s_waitcnt lgkmcnt(0)
	s_barrier
	s_setprio 1
	s_waitcnt lgkmcnt(0)
	v_mfma_f32_16x16x32_bf16 v[60:63], v[130:133], v[202:205], v[60:63]
	v_mfma_f32_16x16x32_bf16 v[56:59], v[138:141], v[202:205], v[56:59]
	v_mfma_f32_16x16x32_bf16 v[44:47], v[130:133], v[210:213], v[44:47]
	v_mfma_f32_16x16x32_bf16 v[40:43], v[138:141], v[210:213], v[40:43]
	v_mfma_f32_16x16x32_bf16 v[28:31], v[130:133], v[218:221], v[28:31]
	v_mfma_f32_16x16x32_bf16 v[24:27], v[138:141], v[218:221], v[24:27]
	v_mfma_f32_16x16x32_bf16 v[12:15], v[130:133], v[226:229], v[12:15]
	v_mfma_f32_16x16x32_bf16 v[8:11], v[138:141], v[226:229], v[8:11]
	v_mfma_f32_16x16x32_bf16 v[60:63], v[134:137], v[206:209], v[60:63]
	v_mfma_f32_16x16x32_bf16 v[56:59], v[142:145], v[206:209], v[56:59]
	v_mfma_f32_16x16x32_bf16 v[44:47], v[134:137], v[214:217], v[44:47]
	v_mfma_f32_16x16x32_bf16 v[40:43], v[142:145], v[214:217], v[40:43]
	v_mfma_f32_16x16x32_bf16 v[28:31], v[134:137], v[222:225], v[28:31]
	v_mfma_f32_16x16x32_bf16 v[24:27], v[142:145], v[222:225], v[24:27]
	v_mfma_f32_16x16x32_bf16 v[12:15], v[134:137], v[238:241], v[12:15]
	v_mfma_f32_16x16x32_bf16 v[8:11], v[142:145], v[238:241], v[8:11]
	v_mfma_f32_16x16x32_bf16 v[52:55], v[158:161], v[202:205], v[52:55]
	v_mfma_f32_16x16x32_bf16 v[48:51], v[166:169], v[202:205], v[48:51]
	v_mfma_f32_16x16x32_bf16 v[36:39], v[158:161], v[210:213], v[36:39]
	v_mfma_f32_16x16x32_bf16 v[32:35], v[166:169], v[210:213], v[32:35]
	v_mfma_f32_16x16x32_bf16 v[20:23], v[158:161], v[218:221], v[20:23]
	v_mfma_f32_16x16x32_bf16 v[16:19], v[166:169], v[218:221], v[16:19]
	v_mfma_f32_16x16x32_bf16 v[4:7], v[158:161], v[226:229], v[4:7]
	v_mfma_f32_16x16x32_bf16 v[0:3], v[166:169], v[226:229], v[0:3]
	v_mfma_f32_16x16x32_bf16 v[52:55], v[162:165], v[206:209], v[52:55]
	v_mfma_f32_16x16x32_bf16 v[48:51], v[198:201], v[206:209], v[48:51]
	v_mfma_f32_16x16x32_bf16 v[36:39], v[162:165], v[214:217], v[36:39]
	v_mfma_f32_16x16x32_bf16 v[32:35], v[198:201], v[214:217], v[32:35]
	v_mfma_f32_16x16x32_bf16 v[20:23], v[162:165], v[222:225], v[20:23]
	v_mfma_f32_16x16x32_bf16 v[16:19], v[198:201], v[222:225], v[16:19]
	v_mfma_f32_16x16x32_bf16 v[4:7], v[162:165], v[238:241], v[4:7]
	v_mfma_f32_16x16x32_bf16 v[0:3], v[198:201], v[238:241], v[0:3]
	s_setprio 0
	s_barrier
	s_add_i32 s61, 0, 0x18000
	v_add_u32_e32 v128, s61, v173
	s_add_i32 vcc_hi, 0, 0x1c000
	ds_read_b128 v[130:133], v128
	ds_read_b128 v[134:137], v128 offset:1024
	ds_read_b128 v[138:141], v128 offset:2048
	ds_read_b128 v[142:145], v128 offset:3072
	v_add_u32_e32 v128, vcc_hi, v173
	ds_read_b128 v[158:161], v128
	ds_read_b128 v[162:165], v128 offset:1024
	ds_read_b128 v[166:169], v128 offset:2048
	ds_read_b128 v[198:201], v128 offset:3072
	s_add_u32 s30, s50, s96
	s_addc_u32 s31, s51, 0
	s_mov_b32 m0, s87
	v_lshl_add_u64 v[252:253], s[30:31], 0, v[146:147]
	ds_read_b128 v[202:205], v190 offset:32768
	ds_read_b128 v[206:209], v190 offset:33792
	ds_read_b128 v[210:213], v190 offset:34816
	ds_read_b128 v[214:217], v190 offset:35840
	ds_read_b128 v[218:221], v190 offset:36864
	ds_read_b128 v[222:225], v190 offset:37888
	ds_read_b128 v[226:229], v190 offset:38912
	ds_read_b128 v[238:241], v190 offset:39936
	global_load_lds_dwordx4 v[252:253], off
	v_lshl_add_u64 v[252:253], s[30:31], 0, v[150:151]
	s_mov_b32 m0, s88
	s_nop 0
	global_load_lds_dwordx4 v[252:253], off
	s_waitcnt vmcnt(8)
	s_waitcnt lgkmcnt(0)
	s_barrier
	s_setprio 1
	s_waitcnt lgkmcnt(0)
	v_mfma_f32_16x16x32_bf16 v[124:127], v[130:133], v[202:205], v[124:127]
	v_mfma_f32_16x16x32_bf16 v[120:123], v[138:141], v[202:205], v[120:123]
	v_mfma_f32_16x16x32_bf16 v[108:111], v[130:133], v[210:213], v[108:111]
	v_mfma_f32_16x16x32_bf16 v[104:107], v[138:141], v[210:213], v[104:107]
	v_mfma_f32_16x16x32_bf16 v[92:95], v[130:133], v[218:221], v[92:95]
	v_mfma_f32_16x16x32_bf16 v[88:91], v[138:141], v[218:221], v[88:91]
	v_mfma_f32_16x16x32_bf16 v[76:79], v[130:133], v[226:229], v[76:79]
	v_mfma_f32_16x16x32_bf16 v[72:75], v[138:141], v[226:229], v[72:75]
	v_mfma_f32_16x16x32_bf16 v[124:127], v[134:137], v[206:209], v[124:127]
	v_mfma_f32_16x16x32_bf16 v[120:123], v[142:145], v[206:209], v[120:123]
	v_mfma_f32_16x16x32_bf16 v[108:111], v[134:137], v[214:217], v[108:111]
	v_mfma_f32_16x16x32_bf16 v[104:107], v[142:145], v[214:217], v[104:107]
	v_mfma_f32_16x16x32_bf16 v[92:95], v[134:137], v[222:225], v[92:95]
	v_mfma_f32_16x16x32_bf16 v[88:91], v[142:145], v[222:225], v[88:91]
	v_mfma_f32_16x16x32_bf16 v[76:79], v[134:137], v[238:241], v[76:79]
	v_mfma_f32_16x16x32_bf16 v[72:75], v[142:145], v[238:241], v[72:75]
	v_mfma_f32_16x16x32_bf16 v[116:119], v[158:161], v[202:205], v[116:119]
	v_mfma_f32_16x16x32_bf16 v[112:115], v[166:169], v[202:205], v[112:115]
	v_mfma_f32_16x16x32_bf16 v[100:103], v[158:161], v[210:213], v[100:103]
	v_mfma_f32_16x16x32_bf16 v[96:99], v[166:169], v[210:213], v[96:99]
	v_mfma_f32_16x16x32_bf16 v[84:87], v[158:161], v[218:221], v[84:87]
	v_mfma_f32_16x16x32_bf16 v[80:83], v[166:169], v[218:221], v[80:83]
	v_mfma_f32_16x16x32_bf16 v[68:71], v[158:161], v[226:229], v[68:71]
	v_mfma_f32_16x16x32_bf16 v[64:67], v[166:169], v[226:229], v[64:67]
	v_mfma_f32_16x16x32_bf16 v[116:119], v[162:165], v[206:209], v[116:119]
	v_mfma_f32_16x16x32_bf16 v[112:115], v[198:201], v[206:209], v[112:115]
	v_mfma_f32_16x16x32_bf16 v[100:103], v[162:165], v[214:217], v[100:103]
	v_mfma_f32_16x16x32_bf16 v[96:99], v[198:201], v[214:217], v[96:99]
	v_mfma_f32_16x16x32_bf16 v[84:87], v[162:165], v[222:225], v[84:87]
	v_mfma_f32_16x16x32_bf16 v[80:83], v[198:201], v[222:225], v[80:83]
	v_mfma_f32_16x16x32_bf16 v[68:71], v[162:165], v[238:241], v[68:71]
	v_mfma_f32_16x16x32_bf16 v[64:67], v[198:201], v[238:241], v[64:67]
	s_setprio 0
	s_barrier
	s_add_i32 s30, s61, s82
	v_lshl_add_u64 v[170:171], v[170:171], 0, s[90:91]
	s_mov_b32 m0, s30
	ds_read_b128 v[202:205], v190 offset:49152
	ds_read_b128 v[206:209], v190 offset:50176
	ds_read_b128 v[210:213], v190 offset:51200
	ds_read_b128 v[214:217], v190 offset:52224
	ds_read_b128 v[218:221], v190 offset:53248
	ds_read_b128 v[222:225], v190 offset:54272
	ds_read_b128 v[226:229], v190 offset:55296
	ds_read_b128 v[238:241], v190 offset:56320
	global_load_lds_dwordx4 v[170:171], off
	v_lshl_add_u64 v[170:171], v[242:243], 0, s[90:91]
	s_add_i32 m0, s30, 0x2000
	s_add_i32 s30, vcc_hi, s82
	global_load_lds_dwordx4 v[170:171], off
	v_lshl_add_u64 v[170:171], v[244:245], 0, s[90:91]
	s_mov_b32 m0, s30
	s_nop 0
	global_load_lds_dwordx4 v[170:171], off
	v_lshl_add_u64 v[170:171], v[246:247], 0, s[90:91]
	s_add_i32 m0, s30, 0x2000
	s_nop 0
	global_load_lds_dwordx4 v[170:171], off
	v_lshl_add_u64 v[170:171], v[248:249], 0, s[90:91]
	s_mov_b32 m0, s53
	s_nop 0
	global_load_lds_dwordx4 v[170:171], off
	v_lshl_add_u64 v[170:171], v[250:251], 0, s[90:91]
	s_mov_b32 m0, s92
	s_nop 0
	global_load_lds_dwordx4 v[170:171], off
	s_waitcnt vmcnt(8)
	s_waitcnt lgkmcnt(0)
	s_barrier
	s_setprio 1
	s_waitcnt lgkmcnt(0)
	v_mfma_f32_16x16x32_bf16 v[60:63], v[130:133], v[202:205], v[60:63]
	v_mfma_f32_16x16x32_bf16 v[56:59], v[138:141], v[202:205], v[56:59]
	v_mfma_f32_16x16x32_bf16 v[44:47], v[130:133], v[210:213], v[44:47]
	v_mfma_f32_16x16x32_bf16 v[40:43], v[138:141], v[210:213], v[40:43]
	v_mfma_f32_16x16x32_bf16 v[28:31], v[130:133], v[218:221], v[28:31]
	v_mfma_f32_16x16x32_bf16 v[24:27], v[138:141], v[218:221], v[24:27]
	v_mfma_f32_16x16x32_bf16 v[12:15], v[130:133], v[226:229], v[12:15]
	v_mfma_f32_16x16x32_bf16 v[8:11], v[138:141], v[226:229], v[8:11]
	v_mfma_f32_16x16x32_bf16 v[60:63], v[134:137], v[206:209], v[60:63]
	v_mfma_f32_16x16x32_bf16 v[56:59], v[142:145], v[206:209], v[56:59]
	v_mfma_f32_16x16x32_bf16 v[44:47], v[134:137], v[214:217], v[44:47]
	v_mfma_f32_16x16x32_bf16 v[40:43], v[142:145], v[214:217], v[40:43]
	v_mfma_f32_16x16x32_bf16 v[28:31], v[134:137], v[222:225], v[28:31]
	v_mfma_f32_16x16x32_bf16 v[24:27], v[142:145], v[222:225], v[24:27]
	v_mfma_f32_16x16x32_bf16 v[12:15], v[134:137], v[238:241], v[12:15]
	v_mfma_f32_16x16x32_bf16 v[8:11], v[142:145], v[238:241], v[8:11]
	v_mfma_f32_16x16x32_bf16 v[52:55], v[158:161], v[202:205], v[52:55]
	v_mfma_f32_16x16x32_bf16 v[48:51], v[166:169], v[202:205], v[48:51]
	v_mfma_f32_16x16x32_bf16 v[36:39], v[158:161], v[210:213], v[36:39]
	v_mfma_f32_16x16x32_bf16 v[32:35], v[166:169], v[210:213], v[32:35]
	v_mfma_f32_16x16x32_bf16 v[20:23], v[158:161], v[218:221], v[20:23]
	v_mfma_f32_16x16x32_bf16 v[16:19], v[166:169], v[218:221], v[16:19]
	v_mfma_f32_16x16x32_bf16 v[4:7], v[158:161], v[226:229], v[4:7]
	v_mfma_f32_16x16x32_bf16 v[0:3], v[166:169], v[226:229], v[0:3]
	v_mfma_f32_16x16x32_bf16 v[52:55], v[162:165], v[206:209], v[52:55]
	v_mfma_f32_16x16x32_bf16 v[48:51], v[198:201], v[206:209], v[48:51]
	v_mfma_f32_16x16x32_bf16 v[36:39], v[162:165], v[214:217], v[36:39]
	v_mfma_f32_16x16x32_bf16 v[32:35], v[198:201], v[214:217], v[32:35]
	v_mfma_f32_16x16x32_bf16 v[20:23], v[162:165], v[222:225], v[20:23]
	v_mfma_f32_16x16x32_bf16 v[16:19], v[198:201], v[222:225], v[16:19]
	v_mfma_f32_16x16x32_bf16 v[4:7], v[162:165], v[238:241], v[4:7]
	v_mfma_f32_16x16x32_bf16 v[0:3], v[198:201], v[238:241], v[0:3]
	s_setprio 0
	s_barrier
	s_add_u32 s45, s45, 0x100
	s_addc_u32 vcc_lo, vcc_lo, 0
	s_add_u32 s8, s8, 0x100
	s_addc_u32 s9, s9, 0
	s_cmp_ge_i32 s60, s5
	s_mov_b32 s50, s60
	s_cbranch_scc0 .LBB0_451

.LBB0_638:
	s_add_u32 s26, s24, 0xfffc0080
	s_addc_u32 s27, s25, -1
	s_add_i32 s30, 0, 0x10000
	s_cmp_eq_u32 s51, 12
	s_cselect_b32 s29, s15, s27
	s_cselect_b32 s28, s21, s26
	s_cselect_b32 s27, s13, s50
	s_cselect_b32 s26, s23, s49
	s_add_i32 s31, 0, 0x14000
	v_add_u32_e32 v156, s30, v145
	v_add_u32_e32 v172, s31, v145
	ds_read_b128 v[140:143], v156
	ds_read_b128 v[148:151], v156 offset:1024
	ds_read_b128 v[152:155], v156 offset:2048
	ds_read_b128 v[156:159], v156 offset:3072
	ds_read_b128 v[160:163], v172
	ds_read_b128 v[164:167], v172 offset:1024
	ds_read_b128 v[168:171], v172 offset:2048
	ds_read_b128 v[172:175], v172 offset:3072
	v_lshl_add_u64 v[176:177], s[24:25], 0, v[138:139]
	s_add_i32 m0, s1, 0xc000
	ds_read_b128 v[198:201], v147
	ds_read_b128 v[202:205], v147 offset:1024
	ds_read_b128 v[206:209], v147 offset:2048
	ds_read_b128 v[210:213], v147 offset:3072
	ds_read_b128 v[214:217], v147 offset:4096
	ds_read_b128 v[218:221], v147 offset:5120
	ds_read_b128 v[222:225], v147 offset:6144
	ds_read_b128 v[226:229], v147 offset:7168
	global_load_lds_dwordx4 v[176:177], off
	v_lshl_add_u64 v[176:177], s[24:25], 0, v[136:137]
	s_add_i32 m0, s1, 0xe000
	s_nop 0
	global_load_lds_dwordx4 v[176:177], off
	s_waitcnt vmcnt(8)
	s_waitcnt lgkmcnt(0)
	s_barrier
	s_setprio 1
	s_waitcnt lgkmcnt(0)
	v_mfma_f32_16x16x32_bf16 v[120:123], v[140:143], v[198:201], v[120:123]
	v_mfma_f32_16x16x32_bf16 v[112:115], v[152:155], v[198:201], v[112:115]
	v_mfma_f32_16x16x32_bf16 v[104:107], v[140:143], v[206:209], v[104:107]
	v_mfma_f32_16x16x32_bf16 v[96:99], v[152:155], v[206:209], v[96:99]
	v_mfma_f32_16x16x32_bf16 v[88:91], v[140:143], v[214:217], v[88:91]
	v_mfma_f32_16x16x32_bf16 v[80:83], v[152:155], v[214:217], v[80:83]
	v_mfma_f32_16x16x32_bf16 v[72:75], v[140:143], v[222:225], v[72:75]
	v_mfma_f32_16x16x32_bf16 v[64:67], v[152:155], v[222:225], v[64:67]
	v_mfma_f32_16x16x32_bf16 v[120:123], v[148:151], v[202:205], v[120:123]
	v_mfma_f32_16x16x32_bf16 v[112:115], v[156:159], v[202:205], v[112:115]
	v_mfma_f32_16x16x32_bf16 v[104:107], v[148:151], v[210:213], v[104:107]
	v_mfma_f32_16x16x32_bf16 v[96:99], v[156:159], v[210:213], v[96:99]
	v_mfma_f32_16x16x32_bf16 v[88:91], v[148:151], v[218:221], v[88:91]
	v_mfma_f32_16x16x32_bf16 v[80:83], v[156:159], v[218:221], v[80:83]
	v_mfma_f32_16x16x32_bf16 v[72:75], v[148:151], v[226:229], v[72:75]
	v_mfma_f32_16x16x32_bf16 v[64:67], v[156:159], v[226:229], v[64:67]
	v_mfma_f32_16x16x32_bf16 v[124:127], v[160:163], v[198:201], v[124:127]
	v_mfma_f32_16x16x32_bf16 v[116:119], v[168:171], v[198:201], v[116:119]
	v_mfma_f32_16x16x32_bf16 v[108:111], v[160:163], v[206:209], v[108:111]
	v_mfma_f32_16x16x32_bf16 v[100:103], v[168:171], v[206:209], v[100:103]
	v_mfma_f32_16x16x32_bf16 v[92:95], v[160:163], v[214:217], v[92:95]
	v_mfma_f32_16x16x32_bf16 v[84:87], v[168:171], v[214:217], v[84:87]
	v_mfma_f32_16x16x32_bf16 v[76:79], v[160:163], v[222:225], v[76:79]
	v_mfma_f32_16x16x32_bf16 v[68:71], v[168:171], v[222:225], v[68:71]
	v_mfma_f32_16x16x32_bf16 v[124:127], v[164:167], v[202:205], v[124:127]
	v_mfma_f32_16x16x32_bf16 v[116:119], v[172:175], v[202:205], v[116:119]
	v_mfma_f32_16x16x32_bf16 v[108:111], v[164:167], v[210:213], v[108:111]
	v_mfma_f32_16x16x32_bf16 v[100:103], v[172:175], v[210:213], v[100:103]
	v_mfma_f32_16x16x32_bf16 v[92:95], v[164:167], v[218:221], v[92:95]
	v_mfma_f32_16x16x32_bf16 v[84:87], v[172:175], v[218:221], v[84:87]
	v_mfma_f32_16x16x32_bf16 v[76:79], v[164:167], v[226:229], v[76:79]
	v_mfma_f32_16x16x32_bf16 v[68:71], v[172:175], v[226:229], v[68:71]
	s_setprio 0
	s_barrier
	s_add_i32 s30, s30, s45
	v_lshl_add_u64 v[176:177], s[26:27], 0, v[128:129]
	s_mov_b32 m0, s30
	ds_read_b128 v[198:201], v147 offset:16384
	ds_read_b128 v[202:205], v147 offset:17408
	ds_read_b128 v[206:209], v147 offset:18432
	ds_read_b128 v[210:213], v147 offset:19456
	ds_read_b128 v[214:217], v147 offset:20480
	ds_read_b128 v[218:221], v147 offset:21504
	ds_read_b128 v[222:225], v147 offset:22528
	ds_read_b128 v[226:229], v147 offset:23552
	global_load_lds_dwordx4 v[176:177], off
	s_add_i32 m0, s30, 0x2000
	s_add_u32 s52, s26, 0x40000
	v_lshl_add_u64 v[238:239], s[26:27], 0, v[130:131]
	s_addc_u32 s53, s27, 0
	s_add_i32 s30, s31, s45
	global_load_lds_dwordx4 v[238:239], off
	v_lshl_add_u64 v[240:241], s[52:53], 0, v[128:129]
	s_mov_b32 m0, s30
	v_lshl_add_u64 v[242:243], s[28:29], 0, v[132:133]
	global_load_lds_dwordx4 v[240:241], off
	v_lshl_add_u64 v[240:241], s[52:53], 0, v[130:131]
	s_add_i32 m0, s30, 0x2000
	s_nop 0
	global_load_lds_dwordx4 v[240:241], off
	v_lshl_add_u64 v[240:241], s[28:29], 0, v[134:135]
	s_mov_b32 m0, s1
	s_nop 0
	global_load_lds_dwordx4 v[240:241], off
	s_mov_b32 m0, s43
	s_nop 0
	global_load_lds_dwordx4 v[242:243], off
	s_waitcnt vmcnt(8)
	s_waitcnt lgkmcnt(0)
	s_barrier
	s_setprio 1
	s_waitcnt lgkmcnt(0)
	v_mfma_f32_16x16x32_bf16 v[56:59], v[140:143], v[198:201], v[56:59]
	v_mfma_f32_16x16x32_bf16 v[48:51], v[152:155], v[198:201], v[48:51]
	v_mfma_f32_16x16x32_bf16 v[40:43], v[140:143], v[206:209], v[40:43]
	v_mfma_f32_16x16x32_bf16 v[32:35], v[152:155], v[206:209], v[32:35]
	v_mfma_f32_16x16x32_bf16 v[24:27], v[140:143], v[214:217], v[24:27]
	v_mfma_f32_16x16x32_bf16 v[16:19], v[152:155], v[214:217], v[16:19]
	v_mfma_f32_16x16x32_bf16 v[8:11], v[140:143], v[222:225], v[8:11]
	v_mfma_f32_16x16x32_bf16 v[0:3], v[152:155], v[222:225], v[0:3]
	v_mfma_f32_16x16x32_bf16 v[56:59], v[148:151], v[202:205], v[56:59]
	v_mfma_f32_16x16x32_bf16 v[48:51], v[156:159], v[202:205], v[48:51]
	v_mfma_f32_16x16x32_bf16 v[40:43], v[148:151], v[210:213], v[40:43]
	v_mfma_f32_16x16x32_bf16 v[32:35], v[156:159], v[210:213], v[32:35]
	v_mfma_f32_16x16x32_bf16 v[24:27], v[148:151], v[218:221], v[24:27]
	v_mfma_f32_16x16x32_bf16 v[16:19], v[156:159], v[218:221], v[16:19]
	v_mfma_f32_16x16x32_bf16 v[8:11], v[148:151], v[226:229], v[8:11]
	v_mfma_f32_16x16x32_bf16 v[0:3], v[156:159], v[226:229], v[0:3]
	v_mfma_f32_16x16x32_bf16 v[60:63], v[160:163], v[198:201], v[60:63]
	v_mfma_f32_16x16x32_bf16 v[52:55], v[168:171], v[198:201], v[52:55]
	v_mfma_f32_16x16x32_bf16 v[44:47], v[160:163], v[206:209], v[44:47]
	v_mfma_f32_16x16x32_bf16 v[36:39], v[168:171], v[206:209], v[36:39]
	v_mfma_f32_16x16x32_bf16 v[28:31], v[160:163], v[214:217], v[28:31]
	v_mfma_f32_16x16x32_bf16 v[20:23], v[168:171], v[214:217], v[20:23]
	v_mfma_f32_16x16x32_bf16 v[12:15], v[160:163], v[222:225], v[12:15]
	v_mfma_f32_16x16x32_bf16 v[4:7], v[168:171], v[222:225], v[4:7]
	v_mfma_f32_16x16x32_bf16 v[60:63], v[164:167], v[202:205], v[60:63]
	v_mfma_f32_16x16x32_bf16 v[52:55], v[172:175], v[202:205], v[52:55]
	v_mfma_f32_16x16x32_bf16 v[44:47], v[164:167], v[210:213], v[44:47]
	v_mfma_f32_16x16x32_bf16 v[36:39], v[172:175], v[210:213], v[36:39]
	v_mfma_f32_16x16x32_bf16 v[28:31], v[164:167], v[218:221], v[28:31]
	v_mfma_f32_16x16x32_bf16 v[20:23], v[172:175], v[218:221], v[20:23]
	v_mfma_f32_16x16x32_bf16 v[12:15], v[164:167], v[226:229], v[12:15]
	v_mfma_f32_16x16x32_bf16 v[4:7], v[172:175], v[226:229], v[4:7]
	s_setprio 0
	s_barrier
	s_add_i32 s30, 0, 0x18000
	s_add_i32 s31, 0, 0x1c000
	v_add_u32_e32 v156, s30, v145
	v_add_u32_e32 v172, s31, v145
	ds_read_b128 v[140:143], v156
	ds_read_b128 v[148:151], v156 offset:1024
	ds_read_b128 v[152:155], v156 offset:2048
	ds_read_b128 v[156:159], v156 offset:3072
	ds_read_b128 v[160:163], v172
	ds_read_b128 v[164:167], v172 offset:1024
	ds_read_b128 v[168:171], v172 offset:2048
	ds_read_b128 v[172:175], v172 offset:3072
	s_add_u32 s28, s28, 0x40000
	s_addc_u32 s29, s29, 0
	s_mov_b32 m0, s46
	v_lshl_add_u64 v[244:245], s[28:29], 0, v[134:135]
	ds_read_b128 v[198:201], v147 offset:32768
	ds_read_b128 v[202:205], v147 offset:33792
	ds_read_b128 v[206:209], v147 offset:34816
	ds_read_b128 v[210:213], v147 offset:35840
	ds_read_b128 v[214:217], v147 offset:36864
	ds_read_b128 v[218:221], v147 offset:37888
	ds_read_b128 v[222:225], v147 offset:38912
	ds_read_b128 v[226:229], v147 offset:39936
	global_load_lds_dwordx4 v[244:245], off
	v_lshl_add_u64 v[244:245], s[28:29], 0, v[132:133]
	s_mov_b32 m0, s47
	s_nop 0
	global_load_lds_dwordx4 v[244:245], off
	s_waitcnt vmcnt(8)
	s_waitcnt lgkmcnt(0)
	s_barrier
	s_setprio 1
	s_waitcnt lgkmcnt(0)
	v_mfma_f32_16x16x32_bf16 v[120:123], v[140:143], v[198:201], v[120:123]
	v_mfma_f32_16x16x32_bf16 v[112:115], v[152:155], v[198:201], v[112:115]
	v_mfma_f32_16x16x32_bf16 v[104:107], v[140:143], v[206:209], v[104:107]
	v_mfma_f32_16x16x32_bf16 v[96:99], v[152:155], v[206:209], v[96:99]
	v_mfma_f32_16x16x32_bf16 v[88:91], v[140:143], v[214:217], v[88:91]
	v_mfma_f32_16x16x32_bf16 v[80:83], v[152:155], v[214:217], v[80:83]
	v_mfma_f32_16x16x32_bf16 v[72:75], v[140:143], v[222:225], v[72:75]
	v_mfma_f32_16x16x32_bf16 v[64:67], v[152:155], v[222:225], v[64:67]
	v_mfma_f32_16x16x32_bf16 v[120:123], v[148:151], v[202:205], v[120:123]
	v_mfma_f32_16x16x32_bf16 v[112:115], v[156:159], v[202:205], v[112:115]
	v_mfma_f32_16x16x32_bf16 v[104:107], v[148:151], v[210:213], v[104:107]
	v_mfma_f32_16x16x32_bf16 v[96:99], v[156:159], v[210:213], v[96:99]
	v_mfma_f32_16x16x32_bf16 v[88:91], v[148:151], v[218:221], v[88:91]
	v_mfma_f32_16x16x32_bf16 v[80:83], v[156:159], v[218:221], v[80:83]
	v_mfma_f32_16x16x32_bf16 v[72:75], v[148:151], v[226:229], v[72:75]
	v_mfma_f32_16x16x32_bf16 v[64:67], v[156:159], v[226:229], v[64:67]
	v_mfma_f32_16x16x32_bf16 v[124:127], v[160:163], v[198:201], v[124:127]
	v_mfma_f32_16x16x32_bf16 v[116:119], v[168:171], v[198:201], v[116:119]
	v_mfma_f32_16x16x32_bf16 v[108:111], v[160:163], v[206:209], v[108:111]
	v_mfma_f32_16x16x32_bf16 v[100:103], v[168:171], v[206:209], v[100:103]
	v_mfma_f32_16x16x32_bf16 v[92:95], v[160:163], v[214:217], v[92:95]
	v_mfma_f32_16x16x32_bf16 v[84:87], v[168:171], v[214:217], v[84:87]
	v_mfma_f32_16x16x32_bf16 v[76:79], v[160:163], v[222:225], v[76:79]
	v_mfma_f32_16x16x32_bf16 v[68:71], v[168:171], v[222:225], v[68:71]
	v_mfma_f32_16x16x32_bf16 v[124:127], v[164:167], v[202:205], v[124:127]
	v_mfma_f32_16x16x32_bf16 v[116:119], v[172:175], v[202:205], v[116:119]
	v_mfma_f32_16x16x32_bf16 v[108:111], v[164:167], v[210:213], v[108:111]
	v_mfma_f32_16x16x32_bf16 v[100:103], v[172:175], v[210:213], v[100:103]
	v_mfma_f32_16x16x32_bf16 v[92:95], v[164:167], v[218:221], v[92:95]
	v_mfma_f32_16x16x32_bf16 v[84:87], v[172:175], v[218:221], v[84:87]
	v_mfma_f32_16x16x32_bf16 v[76:79], v[164:167], v[226:229], v[76:79]
	v_mfma_f32_16x16x32_bf16 v[68:71], v[172:175], v[226:229], v[68:71]
	s_setprio 0
	s_barrier
	s_add_i32 s28, s30, s45
	v_lshl_add_u64 v[176:177], v[176:177], 0, s[90:91]
	s_mov_b32 m0, s28
	ds_read_b128 v[198:201], v147 offset:49152
	ds_read_b128 v[202:205], v147 offset:50176
	ds_read_b128 v[206:209], v147 offset:51200
	ds_read_b128 v[210:213], v147 offset:52224
	ds_read_b128 v[214:217], v147 offset:53248
	ds_read_b128 v[218:221], v147 offset:54272
	ds_read_b128 v[222:225], v147 offset:55296
	ds_read_b128 v[226:229], v147 offset:56320
	global_load_lds_dwordx4 v[176:177], off
	s_add_i32 m0, s28, 0x2000
	s_add_u32 s26, s26, 0x40080
	v_lshl_add_u64 v[176:177], v[238:239], 0, s[90:91]
	s_addc_u32 s27, s27, 0
	s_add_i32 s28, s31, s45
	global_load_lds_dwordx4 v[176:177], off
	v_lshl_add_u64 v[176:177], s[26:27], 0, v[128:129]
	s_mov_b32 m0, s28
	s_nop 0
	global_load_lds_dwordx4 v[176:177], off
	v_lshl_add_u64 v[176:177], s[26:27], 0, v[130:131]
	s_add_i32 m0, s28, 0x2000
	s_nop 0
	global_load_lds_dwordx4 v[176:177], off
	v_lshl_add_u64 v[176:177], v[240:241], 0, s[90:91]
	s_mov_b32 m0, s0
	s_nop 0
	global_load_lds_dwordx4 v[176:177], off
	v_lshl_add_u64 v[176:177], v[242:243], 0, s[90:91]
	s_mov_b32 m0, s4
	s_nop 0
	global_load_lds_dwordx4 v[176:177], off
	s_waitcnt vmcnt(8)
	s_waitcnt lgkmcnt(0)
	s_barrier
	s_setprio 1
	s_waitcnt lgkmcnt(0)
	v_mfma_f32_16x16x32_bf16 v[56:59], v[140:143], v[198:201], v[56:59]
	v_mfma_f32_16x16x32_bf16 v[48:51], v[152:155], v[198:201], v[48:51]
	v_mfma_f32_16x16x32_bf16 v[40:43], v[140:143], v[206:209], v[40:43]
	v_mfma_f32_16x16x32_bf16 v[32:35], v[152:155], v[206:209], v[32:35]
	v_mfma_f32_16x16x32_bf16 v[24:27], v[140:143], v[214:217], v[24:27]
	v_mfma_f32_16x16x32_bf16 v[16:19], v[152:155], v[214:217], v[16:19]
	v_mfma_f32_16x16x32_bf16 v[8:11], v[140:143], v[222:225], v[8:11]
	v_mfma_f32_16x16x32_bf16 v[0:3], v[152:155], v[222:225], v[0:3]
	v_mfma_f32_16x16x32_bf16 v[56:59], v[148:151], v[202:205], v[56:59]
	v_mfma_f32_16x16x32_bf16 v[48:51], v[156:159], v[202:205], v[48:51]
	v_mfma_f32_16x16x32_bf16 v[40:43], v[148:151], v[210:213], v[40:43]
	v_mfma_f32_16x16x32_bf16 v[32:35], v[156:159], v[210:213], v[32:35]
	v_mfma_f32_16x16x32_bf16 v[24:27], v[148:151], v[218:221], v[24:27]
	v_mfma_f32_16x16x32_bf16 v[16:19], v[156:159], v[218:221], v[16:19]
	v_mfma_f32_16x16x32_bf16 v[8:11], v[148:151], v[226:229], v[8:11]
	v_mfma_f32_16x16x32_bf16 v[0:3], v[156:159], v[226:229], v[0:3]
	v_mfma_f32_16x16x32_bf16 v[60:63], v[160:163], v[198:201], v[60:63]
	v_mfma_f32_16x16x32_bf16 v[52:55], v[168:171], v[198:201], v[52:55]
	v_mfma_f32_16x16x32_bf16 v[44:47], v[160:163], v[206:209], v[44:47]
	v_mfma_f32_16x16x32_bf16 v[36:39], v[168:171], v[206:209], v[36:39]
	v_mfma_f32_16x16x32_bf16 v[28:31], v[160:163], v[214:217], v[28:31]
	v_mfma_f32_16x16x32_bf16 v[20:23], v[168:171], v[214:217], v[20:23]
	v_mfma_f32_16x16x32_bf16 v[12:15], v[160:163], v[222:225], v[12:15]
	v_mfma_f32_16x16x32_bf16 v[4:7], v[168:171], v[222:225], v[4:7]
	v_mfma_f32_16x16x32_bf16 v[60:63], v[164:167], v[202:205], v[60:63]
	v_mfma_f32_16x16x32_bf16 v[52:55], v[172:175], v[202:205], v[52:55]
	v_mfma_f32_16x16x32_bf16 v[44:47], v[164:167], v[210:213], v[44:47]
	v_mfma_f32_16x16x32_bf16 v[36:39], v[172:175], v[210:213], v[36:39]
	v_mfma_f32_16x16x32_bf16 v[28:31], v[164:167], v[218:221], v[28:31]
	v_mfma_f32_16x16x32_bf16 v[20:23], v[172:175], v[218:221], v[20:23]
	v_mfma_f32_16x16x32_bf16 v[12:15], v[164:167], v[226:229], v[12:15]
	v_mfma_f32_16x16x32_bf16 v[4:7], v[172:175], v[226:229], v[4:7]
	s_setprio 0
	s_barrier
	s_add_i32 s51, s51, 2
	s_add_u32 s49, s49, 0x100
	s_addc_u32 s50, s50, 0
	s_add_u32 s24, s24, 0x100
	s_addc_u32 s25, s25, 0
	s_cmp_gt_u32 s51, 13
	s_cbranch_scc0 .LBB0_638
	s_and_b64 vcc, exec, s[10:11]
	s_cbranch_vccz .LBB0_641
	s_barrier
